# epilogue f32 divisions via v_rcp_f32+v_mul_f32 (gate-up silu, in-proj gelu/sigmoid incl. interleaved sequences); attention stash in VGPRs
# baseline (speedup 1.0000x reference)
.LBB0_231:
	s_cmp_gt_i32 s8, 1
	s_cselect_b64 s[12:13], -1, 0
	s_cmp_lg_u32 s8, 3
	s_cselect_b64 s[40:41], -1, 0
	s_add_i32 s7, s8, -3
	s_cmp_gt_u32 s7, 1
	s_cselect_b64 s[86:87], -1, 0
	s_lshl_b32 s27, s8, 8
	s_cmp_lg_u32 s8, 2
	s_cselect_b64 s[44:45], -1, 0
	s_cmp_gt_i32 s8, 8
	s_cselect_b64 s[46:47], -1, 0
	s_cmp_lt_i32 s8, 7
	s_movk_i32 s7, 0xfb00
	s_cselect_b32 s42, s7, 0xfffff900
	s_mov_b32 s7, 0x11700000
	s_cselect_b32 s7, s7, 0x12800000
	s_add_u32 s50, s14, s7
	s_addc_u32 s51, s15, 0
	s_cmp_eq_u32 s8, 3
	s_mov_b32 s7, 0x10b00000
	s_cselect_b32 s48, s7, 0x11300000
	s_mov_b32 s7, 0x10700000
	s_cselect_b32 s7, s7, 0x10f00000
	s_add_u32 s31, s14, s7
	s_addc_u32 s35, s15, 0
	s_lshl_b32 s64, s6, 8
	v_readlane_b32 s6, v255, 22
	s_add_i32 s64, s64, s6
	v_or_b32_e32 v172, s64, v155
	v_bitop3_b32 v183, s64, v240, v155 bitop3:0xc8
	v_cmp_gt_i32_e64 s[6:7], s76, v172
	v_or_b32_e32 v170, s27, v184
	v_lshl_add_u64 v[168:169], v[158:159], 0, s[48:49]
	v_cmp_lt_i32_e64 s[8:9], s79, v172
	s_ashr_i32 s26, s64, 13
	v_cndmask_b32_e64 v182, v177, v183, s[6:7]
	s_mov_b64 s[10:11], -1
	s_and_b64 vcc, exec, s[12:13]
	s_cbranch_vccz .LBB0_290
	v_add_u32_e32 v16, 0xffffc000, v172
	s_andn2_b64 vcc, exec, s[86:87]
	s_cbranch_vccnz .LBB0_262
	v_ashrrev_i32_e32 v173, 31, v172
	v_mov_b64_e32 v[130:131], s[14:15]
	s_movk_i32 s10, 0x60
	v_mad_i64_i32 v[136:137], s[10:11], v172, s10, v[130:131]
	v_lshlrev_b64 v[130:131], 10, v[172:173]
	v_lshl_add_u64 v[134:135], s[50:51], 0, v[130:131]
	s_mov_b64 s[10:11], -1
	s_and_b64 vcc, exec, s[44:45]
	s_cbranch_vccz .LBB0_249
	s_and_b64 vcc, exec, s[46:47]
	s_cbranch_vccz .LBB0_238
	s_movk_i32 s10, 0x918
	v_cmp_gt_i32_e32 vcc, s10, v170
	s_and_saveexec_b64 s[10:11], vcc
	s_cbranch_execz .LBB0_237
	v_mul_f32_e32 v132, 0xbfb8aa3b, v128
	v_mul_f32_e32 v133, 0xbfb8aa3b, v129
	v_exp_f32_e32 v132, v132
	v_exp_f32_e32 v133, v133
	v_mul_f32_e32 v130, 0xbfb8aa3b, v126
	v_mul_f32_e32 v131, 0xbfb8aa3b, v127
	v_exp_f32_e32 v130, v130
	v_pk_add_f32 v[132:133], v[132:133], 1.0 op_sel_hi:[1,0]
	v_exp_f32_e32 v131, v131
	s_nop 0
	v_pk_add_f32 v[130:131], v[130:131], 1.0 op_sel_hi:[1,0]
	v_mov_b32_e32 v171, v17
	v_lshl_add_u64 v[138:139], v[170:171], 2, v[136:137]
	v_rcp_f32_e32 v133, v133
	v_rcp_f32_e32 v132, v132
	s_nop 0
	v_rcp_f32_e32 v131, v131
	s_nop 0
	v_mul_f32_e32 v142, 0xbfb8aa3b, v124
	v_mul_f32_e32 v143, 0xbfb8aa3b, v125
	v_exp_f32_e32 v142, v142
	v_exp_f32_e32 v143, v143
	v_rcp_f32_e32 v130, v130
	v_mul_f32_e32 v140, 0xbfb8aa3b, v122
	v_mul_f32_e32 v141, 0xbfb8aa3b, v123
	v_pk_add_f32 v[142:143], v[142:143], 1.0 op_sel_hi:[1,0]
	v_exp_f32_e32 v140, v140
	v_exp_f32_e32 v141, v141
	v_rcp_f32_e32 v143, v143
	v_pk_add_f32 v[140:141], v[140:141], 1.0 op_sel_hi:[1,0]
	v_rcp_f32_e32 v142, v142
	v_rcp_f32_e32 v141, v141
	s_nop 0
	v_add_co_u32_e32 v138, vcc, 0x138fd000, v138
	v_rcp_f32_e32 v140, v140
	s_nop 0
	v_addc_co_u32_e32 v139, vcc, 0, v139, vcc
	global_store_dwordx4 v[138:139], v[130:133], off offset:3072
	global_store_dwordx4 v[138:139], v[140:143], off offset:3088

.LBB0_242:
	s_andn2_b64 vcc, exec, s[46:47]
	s_cbranch_vccnz .LBB0_246
	v_or_b32_e32 v130, 0x80, v170
	s_movk_i32 s10, 0x918
	v_cmp_gt_i32_e32 vcc, s10, v130
	s_and_saveexec_b64 s[10:11], vcc
	s_cbranch_execz .LBB0_245
	v_mul_f32_e32 v132, 0xbfb8aa3b, v120
	v_mul_f32_e32 v133, 0xbfb8aa3b, v121
	v_exp_f32_e32 v132, v132
	v_exp_f32_e32 v133, v133
	v_mul_f32_e32 v130, 0xbfb8aa3b, v118
	v_mul_f32_e32 v131, 0xbfb8aa3b, v119
	v_exp_f32_e32 v130, v130
	v_pk_add_f32 v[132:133], v[132:133], 1.0 op_sel_hi:[1,0]
	v_exp_f32_e32 v131, v131
	s_nop 0
	v_pk_add_f32 v[130:131], v[130:131], 1.0 op_sel_hi:[1,0]
	v_mov_b32_e32 v171, v17
	v_lshl_add_u64 v[136:137], v[170:171], 2, v[136:137]
	v_rcp_f32_e32 v133, v133
	v_rcp_f32_e32 v132, v132
	s_nop 0
	v_rcp_f32_e32 v131, v131
	s_nop 0
	v_rcp_f32_e32 v130, v130
	s_nop 0
	v_mul_f32_e32 v141, 0xbfb8aa3b, v114
	v_exp_f32_e32 v142, v141
	v_mul_f32_e32 v141, 0xbfb8aa3b, v115
	v_exp_f32_e32 v143, v141
	v_mul_f32_e32 v141, 0xbfb8aa3b, v116
	v_exp_f32_e32 v144, v141
	v_mul_f32_e32 v141, 0xbfb8aa3b, v117
	v_exp_f32_e32 v145, v141
	v_pk_add_f32 v[142:143], v[142:143], 1.0 op_sel_hi:[1,0]
	v_pk_add_f32 v[144:145], v[144:145], 1.0 op_sel_hi:[1,0]
	s_nop 0
	v_rcp_f32_e32 v145, v145
	s_nop 0
	v_rcp_f32_e32 v144, v144
	s_nop 0
	v_rcp_f32_e32 v143, v143
	s_nop 0
	v_add_co_u32_e32 v136, vcc, 0x138fd000, v136
	v_rcp_f32_e32 v142, v142
	s_nop 0
	v_addc_co_u32_e32 v137, vcc, 0, v137, vcc
	global_store_dwordx4 v[136:137], v[130:133], off offset:3584
	global_store_dwordx4 v[136:137], v[142:145], off offset:3600

.LBB0_246:
	s_andn2_b64 vcc, exec, s[10:11]
	s_cbranch_vccnz .LBB0_248
	v_mul_f32_e32 v130, 0x3d372713, v118
	v_mul_f32_e32 v130, v118, v130
	v_fma_f32 v130, v118, v130, v118
	v_mul_f32_e32 v130, 0xbfcc422a, v130
	v_mul_f32_e32 v130, 0x3fb8aa3b, v130
	v_exp_f32_e32 v130, v130
	s_ashr_i32 s43, s42, 31
	v_add_f32_e32 v130, 1.0, v130
	v_rcp_f32_e32 v131, v130
	s_nop 0
	v_mul_f32_e32 v130, v118, v131
	v_mul_f32_e32 v131, 0x3d372713, v119
	v_mul_f32_e32 v131, v119, v131
	v_fma_f32 v131, v119, v131, v119
	v_mul_f32_e32 v131, 0xbfcc422a, v131
	v_mul_f32_e32 v131, 0x3fb8aa3b, v131
	v_exp_f32_e32 v131, v131
	s_nop 0
	v_add_f32_e32 v131, 1.0, v131
	v_rcp_f32_e32 v132, v131
	s_nop 0
	v_mul_f32_e32 v131, v119, v132
	v_mul_f32_e32 v132, 0x3d372713, v120
	v_mul_f32_e32 v132, v120, v132
	v_fma_f32 v132, v120, v132, v120
	v_mul_f32_e32 v132, 0xbfcc422a, v132
	v_mul_f32_e32 v132, 0x3fb8aa3b, v132
	v_exp_f32_e32 v132, v132
	v_cvt_pk_bf16_f32 v130, v130, v131
	s_nop 0
	v_add_f32_e32 v132, 1.0, v132
	v_rcp_f32_e32 v133, v132
	s_nop 0
	v_mul_f32_e32 v132, v120, v133
	v_mul_f32_e32 v133, 0x3d372713, v121
	v_mul_f32_e32 v133, v121, v133
	v_fma_f32 v133, v121, v133, v121
	v_mul_f32_e32 v133, 0xbfcc422a, v133
	v_mul_f32_e32 v133, 0x3fb8aa3b, v133
	v_exp_f32_e32 v133, v133
	s_nop 0
	v_add_f32_e32 v133, 1.0, v133
	v_rcp_f32_e32 v136, v133
	s_nop 0
	v_mul_f32_e32 v133, v121, v136
	v_mul_f32_e32 v136, 0x3d372713, v114
	v_mul_f32_e32 v136, v114, v136
	v_fma_f32 v136, v114, v136, v114
	v_mul_f32_e32 v136, 0xbfcc422a, v136
	v_mul_f32_e32 v136, 0x3fb8aa3b, v136
	v_exp_f32_e32 v136, v136
	v_cvt_pk_bf16_f32 v131, v132, v133
	s_nop 0
	v_add_f32_e32 v136, 1.0, v136
	v_rcp_f32_e32 v137, v136
	s_nop 0
	v_mul_f32_e32 v136, v114, v137
	v_mul_f32_e32 v137, 0x3d372713, v115
	v_mul_f32_e32 v137, v115, v137
	v_fma_f32 v137, v115, v137, v115
	v_mul_f32_e32 v137, 0xbfcc422a, v137
	v_mul_f32_e32 v137, 0x3fb8aa3b, v137
	v_exp_f32_e32 v137, v137
	s_nop 0
	v_add_f32_e32 v137, 1.0, v137
	v_rcp_f32_e32 v141, v137
	s_nop 0
	v_mul_f32_e32 v137, v115, v141
	v_mul_f32_e32 v141, 0x3d372713, v116
	v_mul_f32_e32 v141, v116, v141
	v_fma_f32 v141, v116, v141, v116
	v_mul_f32_e32 v141, 0xbfcc422a, v141
	v_mul_f32_e32 v141, 0x3fb8aa3b, v141
	v_exp_f32_e32 v141, v141
	v_cvt_pk_bf16_f32 v132, v136, v137
	s_nop 0
	v_add_f32_e32 v141, 1.0, v141
	v_rcp_f32_e32 v142, v141
	s_nop 0
	v_mul_f32_e32 v141, v116, v142
	v_mul_f32_e32 v142, 0x3d372713, v117
	v_mul_f32_e32 v142, v117, v142
	v_fma_f32 v142, v117, v142, v117
	v_mul_f32_e32 v142, 0xbfcc422a, v142
	v_mul_f32_e32 v142, 0x3fb8aa3b, v142
	v_exp_f32_e32 v142, v142
	s_nop 0
	v_add_f32_e32 v142, 1.0, v142
	v_ashrrev_i32_e32 v171, 31, v170
	v_lshl_add_u64 v[136:137], v[170:171], 0, s[42:43]
	v_readlane_b32 s43, v255, 41
	v_lshl_add_u64 v[134:135], v[136:137], 1, v[134:135]
	v_rcp_f32_e32 v143, v142
	s_nop 0
	v_mul_f32_e32 v142, v117, v143
	v_cvt_pk_bf16_f32 v133, v141, v142
	global_store_dwordx4 v[134:135], v[130:133], off offset:256

.LBB0_292:
	v_or_b32_e32 v132, s64, v185
	v_bitop3_b32 v137, s64, v241, v185 bitop3:0xc8
	v_cmp_gt_i32_e64 s[8:9], s76, v132
	v_cndmask_b32_e64 v16, 0, 1, s[12:13]
	v_cmp_lt_i32_e64 s[10:11], s79, v132
	v_cndmask_b32_e64 v136, v177, v137, s[8:9]
	v_cmp_ne_u32_e64 s[6:7], 1, v16
	s_andn2_b64 vcc, exec, s[12:13]
	s_mov_b64 s[12:13], -1
	s_cbranch_vccnz .LBB0_351
	v_add_u32_e32 v16, 0xffffc000, v132
	s_andn2_b64 vcc, exec, s[86:87]
	s_cbranch_vccnz .LBB0_323
	v_ashrrev_i32_e32 v133, 31, v132
	v_mov_b64_e32 v[114:115], s[14:15]
	s_movk_i32 s12, 0x60
	v_mad_i64_i32 v[120:121], s[12:13], v132, s12, v[114:115]
	v_lshlrev_b64 v[114:115], 10, v[132:133]
	v_lshl_add_u64 v[118:119], s[50:51], 0, v[114:115]
	v_cndmask_b32_e64 v114, 0, 1, s[44:45]
	v_cmp_ne_u32_e64 s[12:13], 1, v114
	s_andn2_b64 vcc, exec, s[44:45]
	s_mov_b64 s[52:53], -1
	s_cbranch_vccnz .LBB0_310
	s_andn2_b64 vcc, exec, s[46:47]
	s_cbranch_vccnz .LBB0_299
	s_movk_i32 s27, 0x918
	v_cmp_gt_i32_e32 vcc, s27, v170
	s_and_saveexec_b64 s[52:53], vcc
	s_cbranch_execz .LBB0_298
	v_mul_f32_e32 v116, 0xbfb8aa3b, v112
	v_mul_f32_e32 v117, 0xbfb8aa3b, v113
	v_exp_f32_e32 v116, v116
	v_exp_f32_e32 v117, v117
	v_mul_f32_e32 v114, 0xbfb8aa3b, v110
	v_mul_f32_e32 v115, 0xbfb8aa3b, v111
	v_exp_f32_e32 v114, v114
	v_pk_add_f32 v[116:117], v[116:117], 1.0 op_sel_hi:[1,0]
	v_exp_f32_e32 v115, v115
	s_nop 0
	v_pk_add_f32 v[114:115], v[114:115], 1.0 op_sel_hi:[1,0]
	v_mov_b32_e32 v171, v17
	v_lshl_add_u64 v[122:123], v[170:171], 2, v[120:121]
	v_rcp_f32_e32 v117, v117
	v_rcp_f32_e32 v116, v116
	s_nop 0
	v_rcp_f32_e32 v115, v115
	s_nop 0
	v_mul_f32_e32 v126, 0xbfb8aa3b, v108
	v_mul_f32_e32 v127, 0xbfb8aa3b, v109
	v_exp_f32_e32 v126, v126
	v_exp_f32_e32 v127, v127
	v_rcp_f32_e32 v114, v114
	v_mul_f32_e32 v124, 0xbfb8aa3b, v106
	v_mul_f32_e32 v125, 0xbfb8aa3b, v107
	v_pk_add_f32 v[126:127], v[126:127], 1.0 op_sel_hi:[1,0]
	v_exp_f32_e32 v124, v124
	v_exp_f32_e32 v125, v125
	v_rcp_f32_e32 v127, v127
	v_pk_add_f32 v[124:125], v[124:125], 1.0 op_sel_hi:[1,0]
	v_rcp_f32_e32 v126, v126
	v_rcp_f32_e32 v125, v125
	s_nop 0
	v_add_co_u32_e32 v122, vcc, 0x138fd000, v122
	v_rcp_f32_e32 v124, v124
	s_nop 0
	v_addc_co_u32_e32 v123, vcc, 0, v123, vcc
	global_store_dwordx4 v[122:123], v[114:117], off offset:3072
	global_store_dwordx4 v[122:123], v[124:127], off offset:3088

.LBB0_303:
	s_andn2_b64 vcc, exec, s[46:47]
	s_cbranch_vccnz .LBB0_307
	v_or_b32_e32 v114, 0x80, v170
	s_movk_i32 s12, 0x918
	v_cmp_gt_i32_e32 vcc, s12, v114
	s_and_saveexec_b64 s[12:13], vcc
	s_cbranch_execz .LBB0_306
	v_mul_f32_e32 v116, 0xbfb8aa3b, v104
	v_mul_f32_e32 v117, 0xbfb8aa3b, v105
	v_exp_f32_e32 v116, v116
	v_exp_f32_e32 v117, v117
	v_mul_f32_e32 v114, 0xbfb8aa3b, v102
	v_mul_f32_e32 v115, 0xbfb8aa3b, v103
	v_exp_f32_e32 v114, v114
	v_pk_add_f32 v[116:117], v[116:117], 1.0 op_sel_hi:[1,0]
	v_exp_f32_e32 v115, v115
	s_nop 0
	v_pk_add_f32 v[114:115], v[114:115], 1.0 op_sel_hi:[1,0]
	v_mov_b32_e32 v171, v17
	v_lshl_add_u64 v[120:121], v[170:171], 2, v[120:121]
	v_rcp_f32_e32 v117, v117
	v_rcp_f32_e32 v116, v116
	s_nop 0
	v_rcp_f32_e32 v115, v115
	s_nop 0
	v_rcp_f32_e32 v114, v114
	s_nop 0
	v_mul_f32_e32 v125, 0xbfb8aa3b, v98
	v_exp_f32_e32 v126, v125
	v_mul_f32_e32 v125, 0xbfb8aa3b, v99
	v_exp_f32_e32 v127, v125
	v_mul_f32_e32 v125, 0xbfb8aa3b, v100
	v_exp_f32_e32 v128, v125
	v_mul_f32_e32 v125, 0xbfb8aa3b, v101
	v_exp_f32_e32 v129, v125
	v_pk_add_f32 v[126:127], v[126:127], 1.0 op_sel_hi:[1,0]
	v_pk_add_f32 v[128:129], v[128:129], 1.0 op_sel_hi:[1,0]
	s_nop 0
	v_rcp_f32_e32 v129, v129
	s_nop 0
	v_rcp_f32_e32 v128, v128
	s_nop 0
	v_rcp_f32_e32 v127, v127
	s_nop 0
	v_add_co_u32_e32 v120, vcc, 0x138fd000, v120
	v_rcp_f32_e32 v126, v126
	s_nop 0
	v_addc_co_u32_e32 v121, vcc, 0, v121, vcc
	global_store_dwordx4 v[120:121], v[114:117], off offset:3584
	global_store_dwordx4 v[120:121], v[126:129], off offset:3600

.LBB0_307:
	s_andn2_b64 vcc, exec, s[12:13]
	s_cbranch_vccnz .LBB0_309
	v_mul_f32_e32 v114, 0x3d372713, v102
	v_mul_f32_e32 v114, v102, v114
	v_fma_f32 v114, v102, v114, v102
	v_mul_f32_e32 v114, 0xbfcc422a, v114
	v_mul_f32_e32 v114, 0x3fb8aa3b, v114
	v_exp_f32_e32 v114, v114
	s_ashr_i32 s43, s42, 31
	v_ashrrev_i32_e32 v171, 31, v170
	v_add_f32_e32 v114, 1.0, v114
	v_rcp_f32_e32 v115, v114
	s_nop 0
	v_mul_f32_e32 v114, v102, v115
	v_mul_f32_e32 v115, 0x3d372713, v103
	v_mul_f32_e32 v115, v103, v115
	v_fma_f32 v115, v103, v115, v103
	v_mul_f32_e32 v115, 0xbfcc422a, v115
	v_mul_f32_e32 v115, 0x3fb8aa3b, v115
	v_exp_f32_e32 v115, v115
	s_nop 0
	v_add_f32_e32 v115, 1.0, v115
	v_rcp_f32_e32 v116, v115
	s_nop 0
	v_mul_f32_e32 v115, v103, v116
	v_mul_f32_e32 v116, 0x3d372713, v104
	v_mul_f32_e32 v116, v104, v116
	v_fma_f32 v116, v104, v116, v104
	v_mul_f32_e32 v116, 0xbfcc422a, v116
	v_mul_f32_e32 v116, 0x3fb8aa3b, v116
	v_exp_f32_e32 v116, v116
	v_cvt_pk_bf16_f32 v114, v114, v115
	s_nop 0
	v_add_f32_e32 v116, 1.0, v116
	v_rcp_f32_e32 v117, v116
	s_nop 0
	v_mul_f32_e32 v116, v104, v117
	v_mul_f32_e32 v117, 0x3d372713, v105
	v_mul_f32_e32 v117, v105, v117
	v_fma_f32 v117, v105, v117, v105
	v_mul_f32_e32 v117, 0xbfcc422a, v117
	v_mul_f32_e32 v117, 0x3fb8aa3b, v117
	v_exp_f32_e32 v117, v117
	s_nop 0
	v_add_f32_e32 v117, 1.0, v117
	v_rcp_f32_e32 v120, v117
	s_nop 0
	v_mul_f32_e32 v117, v105, v120
	v_mul_f32_e32 v120, 0x3d372713, v98
	v_mul_f32_e32 v120, v98, v120
	v_fma_f32 v120, v98, v120, v98
	v_mul_f32_e32 v120, 0xbfcc422a, v120
	v_mul_f32_e32 v120, 0x3fb8aa3b, v120
	v_exp_f32_e32 v120, v120
	v_cvt_pk_bf16_f32 v115, v116, v117
	s_nop 0
	v_add_f32_e32 v120, 1.0, v120
	v_rcp_f32_e32 v121, v120
	s_nop 0
	v_mul_f32_e32 v120, v98, v121
	v_mul_f32_e32 v121, 0x3d372713, v99
	v_mul_f32_e32 v121, v99, v121
	v_fma_f32 v121, v99, v121, v99
	v_mul_f32_e32 v121, 0xbfcc422a, v121
	v_mul_f32_e32 v121, 0x3fb8aa3b, v121
	v_exp_f32_e32 v121, v121
	s_nop 0
	v_add_f32_e32 v121, 1.0, v121
	v_rcp_f32_e32 v125, v121
	s_nop 0
	v_mul_f32_e32 v121, v99, v125
	v_mul_f32_e32 v125, 0x3d372713, v100
	v_mul_f32_e32 v125, v100, v125
	v_fma_f32 v125, v100, v125, v100
	v_mul_f32_e32 v125, 0xbfcc422a, v125
	v_mul_f32_e32 v125, 0x3fb8aa3b, v125
	v_exp_f32_e32 v125, v125
	v_cvt_pk_bf16_f32 v116, v120, v121
	v_lshl_add_u64 v[120:121], v[170:171], 0, s[42:43]
	v_readlane_b32 s43, v255, 41
	v_add_f32_e32 v125, 1.0, v125
	v_lshl_add_u64 v[118:119], v[120:121], 1, v[118:119]
	v_rcp_f32_e32 v126, v125
	s_nop 0
	v_mul_f32_e32 v125, v100, v126
	v_mul_f32_e32 v126, 0x3d372713, v101
	v_mul_f32_e32 v126, v101, v126
	v_fma_f32 v126, v101, v126, v101
	v_mul_f32_e32 v126, 0xbfcc422a, v126
	v_mul_f32_e32 v126, 0x3fb8aa3b, v126
	v_exp_f32_e32 v126, v126
	s_nop 0
	v_add_f32_e32 v126, 1.0, v126
	v_rcp_f32_e32 v127, v126
	s_nop 0
	v_mul_f32_e32 v126, v101, v127
	v_cvt_pk_bf16_f32 v117, v125, v126
	global_store_dwordx4 v[118:119], v[114:117], off offset:256

.LBB0_353:
	v_or_b32_e32 v114, s64, v186
	v_bitop3_b32 v119, s64, v242, v186 bitop3:0xc8
	v_cmp_gt_i32_e64 s[8:9], s76, v114
	v_cmp_lt_i32_e64 s[10:11], s79, v114
	s_and_b64 vcc, exec, s[6:7]
	v_cndmask_b32_e64 v118, v177, v119, s[8:9]
	s_mov_b64 s[12:13], -1
	s_cbranch_vccnz .LBB0_412
	v_add_u32_e32 v16, 0xffffc000, v114
	s_andn2_b64 vcc, exec, s[86:87]
	s_cbranch_vccnz .LBB0_384
	v_ashrrev_i32_e32 v115, 31, v114
	v_mov_b64_e32 v[98:99], s[14:15]
	s_movk_i32 s12, 0x60
	v_mad_i64_i32 v[104:105], s[12:13], v114, s12, v[98:99]
	v_lshlrev_b64 v[98:99], 10, v[114:115]
	v_lshl_add_u64 v[102:103], s[50:51], 0, v[98:99]
	v_cndmask_b32_e64 v98, 0, 1, s[44:45]
	v_cmp_ne_u32_e64 s[12:13], 1, v98
	s_andn2_b64 vcc, exec, s[44:45]
	s_mov_b64 s[52:53], -1
	s_cbranch_vccnz .LBB0_371
	s_andn2_b64 vcc, exec, s[46:47]
	s_cbranch_vccnz .LBB0_360
	s_movk_i32 s27, 0x918
	v_cmp_gt_i32_e32 vcc, s27, v170
	s_and_saveexec_b64 s[52:53], vcc
	s_cbranch_execz .LBB0_359
	v_mul_f32_e32 v100, 0xbfb8aa3b, v96
	v_mul_f32_e32 v101, 0xbfb8aa3b, v97
	v_exp_f32_e32 v100, v100
	v_exp_f32_e32 v101, v101
	v_mul_f32_e32 v98, 0xbfb8aa3b, v94
	v_mul_f32_e32 v99, 0xbfb8aa3b, v95
	v_exp_f32_e32 v98, v98
	v_pk_add_f32 v[100:101], v[100:101], 1.0 op_sel_hi:[1,0]
	v_exp_f32_e32 v99, v99
	s_nop 0
	v_pk_add_f32 v[98:99], v[98:99], 1.0 op_sel_hi:[1,0]
	v_mov_b32_e32 v171, v17
	v_lshl_add_u64 v[106:107], v[170:171], 2, v[104:105]
	v_rcp_f32_e32 v101, v101
	v_rcp_f32_e32 v100, v100
	s_nop 0
	v_rcp_f32_e32 v99, v99
	s_nop 0
	v_mul_f32_e32 v110, 0xbfb8aa3b, v92
	v_mul_f32_e32 v111, 0xbfb8aa3b, v93
	v_exp_f32_e32 v110, v110
	v_exp_f32_e32 v111, v111
	v_rcp_f32_e32 v98, v98
	v_mul_f32_e32 v108, 0xbfb8aa3b, v90
	v_mul_f32_e32 v109, 0xbfb8aa3b, v91
	v_pk_add_f32 v[110:111], v[110:111], 1.0 op_sel_hi:[1,0]
	v_exp_f32_e32 v108, v108
	v_exp_f32_e32 v109, v109
	v_rcp_f32_e32 v111, v111
	v_pk_add_f32 v[108:109], v[108:109], 1.0 op_sel_hi:[1,0]
	v_rcp_f32_e32 v110, v110
	v_rcp_f32_e32 v109, v109
	s_nop 0
	v_add_co_u32_e32 v106, vcc, 0x138fd000, v106
	v_rcp_f32_e32 v108, v108
	s_nop 0
	v_addc_co_u32_e32 v107, vcc, 0, v107, vcc
	global_store_dwordx4 v[106:107], v[98:101], off offset:3072
	global_store_dwordx4 v[106:107], v[108:111], off offset:3088

.LBB0_364:
	s_andn2_b64 vcc, exec, s[46:47]
	s_cbranch_vccnz .LBB0_368
	v_or_b32_e32 v98, 0x80, v170
	s_movk_i32 s12, 0x918
	v_cmp_gt_i32_e32 vcc, s12, v98
	s_and_saveexec_b64 s[12:13], vcc
	s_cbranch_execz .LBB0_367
	v_mul_f32_e32 v100, 0xbfb8aa3b, v88
	v_mul_f32_e32 v101, 0xbfb8aa3b, v89
	v_exp_f32_e32 v100, v100
	v_exp_f32_e32 v101, v101
	v_mul_f32_e32 v98, 0xbfb8aa3b, v86
	v_mul_f32_e32 v99, 0xbfb8aa3b, v87
	v_exp_f32_e32 v98, v98
	v_pk_add_f32 v[100:101], v[100:101], 1.0 op_sel_hi:[1,0]
	v_exp_f32_e32 v99, v99
	s_nop 0
	v_pk_add_f32 v[98:99], v[98:99], 1.0 op_sel_hi:[1,0]
	v_mov_b32_e32 v171, v17
	v_lshl_add_u64 v[104:105], v[170:171], 2, v[104:105]
	v_rcp_f32_e32 v101, v101
	v_rcp_f32_e32 v100, v100
	s_nop 0
	v_rcp_f32_e32 v99, v99
	s_nop 0
	v_rcp_f32_e32 v98, v98
	s_nop 0
	v_mul_f32_e32 v109, 0xbfb8aa3b, v82
	v_exp_f32_e32 v110, v109
	v_mul_f32_e32 v109, 0xbfb8aa3b, v83
	v_exp_f32_e32 v111, v109
	v_mul_f32_e32 v109, 0xbfb8aa3b, v84
	v_exp_f32_e32 v112, v109
	v_mul_f32_e32 v109, 0xbfb8aa3b, v85
	v_exp_f32_e32 v113, v109
	v_pk_add_f32 v[110:111], v[110:111], 1.0 op_sel_hi:[1,0]
	v_pk_add_f32 v[112:113], v[112:113], 1.0 op_sel_hi:[1,0]
	s_nop 0
	v_rcp_f32_e32 v113, v113
	s_nop 0
	v_rcp_f32_e32 v112, v112
	s_nop 0
	v_rcp_f32_e32 v111, v111
	s_nop 0
	v_add_co_u32_e32 v104, vcc, 0x138fd000, v104
	v_rcp_f32_e32 v110, v110
	s_nop 0
	v_addc_co_u32_e32 v105, vcc, 0, v105, vcc
	global_store_dwordx4 v[104:105], v[98:101], off offset:3584
	global_store_dwordx4 v[104:105], v[110:113], off offset:3600

.LBB0_368:
	s_andn2_b64 vcc, exec, s[12:13]
	s_cbranch_vccnz .LBB0_370
	v_mul_f32_e32 v98, 0x3d372713, v86
	v_mul_f32_e32 v98, v86, v98
	v_fma_f32 v98, v86, v98, v86
	v_mul_f32_e32 v98, 0xbfcc422a, v98
	v_mul_f32_e32 v98, 0x3fb8aa3b, v98
	v_exp_f32_e32 v98, v98
	s_ashr_i32 s43, s42, 31
	v_ashrrev_i32_e32 v171, 31, v170
	v_add_f32_e32 v98, 1.0, v98
	v_rcp_f32_e32 v99, v98
	s_nop 0
	v_mul_f32_e32 v98, v86, v99
	v_mul_f32_e32 v99, 0x3d372713, v87
	v_mul_f32_e32 v99, v87, v99
	v_fma_f32 v99, v87, v99, v87
	v_mul_f32_e32 v99, 0xbfcc422a, v99
	v_mul_f32_e32 v99, 0x3fb8aa3b, v99
	v_exp_f32_e32 v99, v99
	s_nop 0
	v_add_f32_e32 v99, 1.0, v99
	v_rcp_f32_e32 v100, v99
	s_nop 0
	v_mul_f32_e32 v99, v87, v100
	v_mul_f32_e32 v100, 0x3d372713, v88
	v_mul_f32_e32 v100, v88, v100
	v_fma_f32 v100, v88, v100, v88
	v_mul_f32_e32 v100, 0xbfcc422a, v100
	v_mul_f32_e32 v100, 0x3fb8aa3b, v100
	v_exp_f32_e32 v100, v100
	v_cvt_pk_bf16_f32 v98, v98, v99
	s_nop 0
	v_add_f32_e32 v100, 1.0, v100
	v_rcp_f32_e32 v101, v100
	s_nop 0
	v_mul_f32_e32 v100, v88, v101
	v_mul_f32_e32 v101, 0x3d372713, v89
	v_mul_f32_e32 v101, v89, v101
	v_fma_f32 v101, v89, v101, v89
	v_mul_f32_e32 v101, 0xbfcc422a, v101
	v_mul_f32_e32 v101, 0x3fb8aa3b, v101
	v_exp_f32_e32 v101, v101
	s_nop 0
	v_add_f32_e32 v101, 1.0, v101
	v_rcp_f32_e32 v104, v101
	s_nop 0
	v_mul_f32_e32 v101, v89, v104
	v_mul_f32_e32 v104, 0x3d372713, v82
	v_mul_f32_e32 v104, v82, v104
	v_fma_f32 v104, v82, v104, v82
	v_mul_f32_e32 v104, 0xbfcc422a, v104
	v_mul_f32_e32 v104, 0x3fb8aa3b, v104
	v_exp_f32_e32 v104, v104
	v_cvt_pk_bf16_f32 v99, v100, v101
	s_nop 0
	v_add_f32_e32 v104, 1.0, v104
	v_rcp_f32_e32 v105, v104
	s_nop 0
	v_mul_f32_e32 v104, v82, v105
	v_mul_f32_e32 v105, 0x3d372713, v83
	v_mul_f32_e32 v105, v83, v105
	v_fma_f32 v105, v83, v105, v83
	v_mul_f32_e32 v105, 0xbfcc422a, v105
	v_mul_f32_e32 v105, 0x3fb8aa3b, v105
	v_exp_f32_e32 v105, v105
	s_nop 0
	v_add_f32_e32 v105, 1.0, v105
	v_rcp_f32_e32 v109, v105
	s_nop 0
	v_mul_f32_e32 v105, v83, v109
	v_mul_f32_e32 v109, 0x3d372713, v84
	v_mul_f32_e32 v109, v84, v109
	v_fma_f32 v109, v84, v109, v84
	v_mul_f32_e32 v109, 0xbfcc422a, v109
	v_mul_f32_e32 v109, 0x3fb8aa3b, v109
	v_exp_f32_e32 v109, v109
	v_cvt_pk_bf16_f32 v100, v104, v105
	v_lshl_add_u64 v[104:105], v[170:171], 0, s[42:43]
	v_readlane_b32 s43, v255, 41
	v_add_f32_e32 v109, 1.0, v109
	v_lshl_add_u64 v[102:103], v[104:105], 1, v[102:103]
	v_rcp_f32_e32 v110, v109
	s_nop 0
	v_mul_f32_e32 v109, v84, v110
	v_mul_f32_e32 v110, 0x3d372713, v85
	v_mul_f32_e32 v110, v85, v110
	v_fma_f32 v110, v85, v110, v85
	v_mul_f32_e32 v110, 0xbfcc422a, v110
	v_mul_f32_e32 v110, 0x3fb8aa3b, v110
	v_exp_f32_e32 v110, v110
	s_nop 0
	v_add_f32_e32 v110, 1.0, v110
	v_rcp_f32_e32 v111, v110
	s_nop 0
	v_mul_f32_e32 v110, v85, v111
	v_cvt_pk_bf16_f32 v101, v109, v110
	global_store_dwordx4 v[102:103], v[98:101], off offset:256

.LBB0_414:
	v_or_b32_e32 v98, s64, v187
	v_bitop3_b32 v103, s64, v243, v187 bitop3:0xc8
	v_cmp_gt_i32_e64 s[8:9], s76, v98
	v_cmp_lt_i32_e64 s[10:11], s79, v98
	s_and_b64 vcc, exec, s[6:7]
	v_cndmask_b32_e64 v102, v177, v103, s[8:9]
	s_mov_b64 s[12:13], -1
	s_cbranch_vccnz .LBB0_473
	v_add_u32_e32 v16, 0xffffc000, v98
	s_andn2_b64 vcc, exec, s[86:87]
	s_cbranch_vccnz .LBB0_445
	v_ashrrev_i32_e32 v99, 31, v98
	v_mov_b64_e32 v[82:83], s[14:15]
	s_movk_i32 s12, 0x60
	v_mad_i64_i32 v[88:89], s[12:13], v98, s12, v[82:83]
	v_lshlrev_b64 v[82:83], 10, v[98:99]
	v_lshl_add_u64 v[86:87], s[50:51], 0, v[82:83]
	v_cndmask_b32_e64 v82, 0, 1, s[44:45]
	v_cmp_ne_u32_e64 s[12:13], 1, v82
	s_andn2_b64 vcc, exec, s[44:45]
	s_mov_b64 s[52:53], -1
	s_cbranch_vccnz .LBB0_432
	s_andn2_b64 vcc, exec, s[46:47]
	s_cbranch_vccnz .LBB0_421
	s_movk_i32 s27, 0x918
	v_cmp_gt_i32_e32 vcc, s27, v170
	s_and_saveexec_b64 s[52:53], vcc
	s_cbranch_execz .LBB0_420
	v_mul_f32_e32 v84, 0xbfb8aa3b, v80
	v_mul_f32_e32 v85, 0xbfb8aa3b, v81
	v_exp_f32_e32 v84, v84
	v_exp_f32_e32 v85, v85
	v_mul_f32_e32 v82, 0xbfb8aa3b, v78
	v_mul_f32_e32 v83, 0xbfb8aa3b, v79
	v_exp_f32_e32 v82, v82
	v_pk_add_f32 v[84:85], v[84:85], 1.0 op_sel_hi:[1,0]
	v_exp_f32_e32 v83, v83
	s_nop 0
	v_pk_add_f32 v[82:83], v[82:83], 1.0 op_sel_hi:[1,0]
	v_mov_b32_e32 v171, v17
	v_lshl_add_u64 v[90:91], v[170:171], 2, v[88:89]
	v_rcp_f32_e32 v85, v85
	v_rcp_f32_e32 v84, v84
	s_nop 0
	v_rcp_f32_e32 v83, v83
	s_nop 0
	v_mul_f32_e32 v94, 0xbfb8aa3b, v76
	v_mul_f32_e32 v95, 0xbfb8aa3b, v77
	v_exp_f32_e32 v94, v94
	v_exp_f32_e32 v95, v95
	v_rcp_f32_e32 v82, v82
	v_mul_f32_e32 v92, 0xbfb8aa3b, v74
	v_mul_f32_e32 v93, 0xbfb8aa3b, v75
	v_pk_add_f32 v[94:95], v[94:95], 1.0 op_sel_hi:[1,0]
	v_exp_f32_e32 v92, v92
	v_exp_f32_e32 v93, v93
	v_rcp_f32_e32 v95, v95
	v_pk_add_f32 v[92:93], v[92:93], 1.0 op_sel_hi:[1,0]
	v_rcp_f32_e32 v94, v94
	v_rcp_f32_e32 v93, v93
	s_nop 0
	v_add_co_u32_e32 v90, vcc, 0x138fd000, v90
	v_rcp_f32_e32 v92, v92
	s_nop 0
	v_addc_co_u32_e32 v91, vcc, 0, v91, vcc
	global_store_dwordx4 v[90:91], v[82:85], off offset:3072
	global_store_dwordx4 v[90:91], v[92:95], off offset:3088

.LBB0_425:
	s_andn2_b64 vcc, exec, s[46:47]
	s_cbranch_vccnz .LBB0_429
	v_or_b32_e32 v82, 0x80, v170
	s_movk_i32 s12, 0x918
	v_cmp_gt_i32_e32 vcc, s12, v82
	s_and_saveexec_b64 s[12:13], vcc
	s_cbranch_execz .LBB0_428
	v_mul_f32_e32 v84, 0xbfb8aa3b, v72
	v_mul_f32_e32 v85, 0xbfb8aa3b, v73
	v_exp_f32_e32 v84, v84
	v_exp_f32_e32 v85, v85
	v_mul_f32_e32 v82, 0xbfb8aa3b, v70
	v_mul_f32_e32 v83, 0xbfb8aa3b, v71
	v_exp_f32_e32 v82, v82
	v_pk_add_f32 v[84:85], v[84:85], 1.0 op_sel_hi:[1,0]
	v_exp_f32_e32 v83, v83
	s_nop 0
	v_pk_add_f32 v[82:83], v[82:83], 1.0 op_sel_hi:[1,0]
	v_mov_b32_e32 v171, v17
	v_lshl_add_u64 v[88:89], v[170:171], 2, v[88:89]
	v_rcp_f32_e32 v85, v85
	v_rcp_f32_e32 v84, v84
	s_nop 0
	v_rcp_f32_e32 v83, v83
	s_nop 0
	v_rcp_f32_e32 v82, v82
	s_nop 0
	v_mul_f32_e32 v93, 0xbfb8aa3b, v66
	v_exp_f32_e32 v94, v93
	v_mul_f32_e32 v93, 0xbfb8aa3b, v67
	v_exp_f32_e32 v95, v93
	v_mul_f32_e32 v93, 0xbfb8aa3b, v68
	v_exp_f32_e32 v96, v93
	v_mul_f32_e32 v93, 0xbfb8aa3b, v69
	v_exp_f32_e32 v97, v93
	v_pk_add_f32 v[94:95], v[94:95], 1.0 op_sel_hi:[1,0]
	v_pk_add_f32 v[96:97], v[96:97], 1.0 op_sel_hi:[1,0]
	s_nop 0
	v_rcp_f32_e32 v97, v97
	s_nop 0
	v_rcp_f32_e32 v96, v96
	s_nop 0
	v_rcp_f32_e32 v95, v95
	s_nop 0
	v_add_co_u32_e32 v88, vcc, 0x138fd000, v88
	v_rcp_f32_e32 v94, v94
	s_nop 0
	v_addc_co_u32_e32 v89, vcc, 0, v89, vcc
	global_store_dwordx4 v[88:89], v[82:85], off offset:3584
	global_store_dwordx4 v[88:89], v[94:97], off offset:3600

.LBB0_429:
	s_andn2_b64 vcc, exec, s[12:13]
	s_cbranch_vccnz .LBB0_431
	v_mul_f32_e32 v82, 0x3d372713, v70
	v_mul_f32_e32 v82, v70, v82
	v_fma_f32 v82, v70, v82, v70
	v_mul_f32_e32 v82, 0xbfcc422a, v82
	v_mul_f32_e32 v82, 0x3fb8aa3b, v82
	v_exp_f32_e32 v82, v82
	s_ashr_i32 s43, s42, 31
	v_ashrrev_i32_e32 v171, 31, v170
	v_add_f32_e32 v82, 1.0, v82
	v_rcp_f32_e32 v83, v82
	s_nop 0
	v_mul_f32_e32 v82, v70, v83
	v_mul_f32_e32 v83, 0x3d372713, v71
	v_mul_f32_e32 v83, v71, v83
	v_fma_f32 v83, v71, v83, v71
	v_mul_f32_e32 v83, 0xbfcc422a, v83
	v_mul_f32_e32 v83, 0x3fb8aa3b, v83
	v_exp_f32_e32 v83, v83
	s_nop 0
	v_add_f32_e32 v83, 1.0, v83
	v_rcp_f32_e32 v84, v83
	s_nop 0
	v_mul_f32_e32 v83, v71, v84
	v_mul_f32_e32 v84, 0x3d372713, v72
	v_mul_f32_e32 v84, v72, v84
	v_fma_f32 v84, v72, v84, v72
	v_mul_f32_e32 v84, 0xbfcc422a, v84
	v_mul_f32_e32 v84, 0x3fb8aa3b, v84
	v_exp_f32_e32 v84, v84
	v_cvt_pk_bf16_f32 v82, v82, v83
	s_nop 0
	v_add_f32_e32 v84, 1.0, v84
	v_rcp_f32_e32 v85, v84
	s_nop 0
	v_mul_f32_e32 v84, v72, v85
	v_mul_f32_e32 v85, 0x3d372713, v73
	v_mul_f32_e32 v85, v73, v85
	v_fma_f32 v85, v73, v85, v73
	v_mul_f32_e32 v85, 0xbfcc422a, v85
	v_mul_f32_e32 v85, 0x3fb8aa3b, v85
	v_exp_f32_e32 v85, v85
	s_nop 0
	v_add_f32_e32 v85, 1.0, v85
	v_rcp_f32_e32 v88, v85
	s_nop 0
	v_mul_f32_e32 v85, v73, v88
	v_mul_f32_e32 v88, 0x3d372713, v66
	v_mul_f32_e32 v88, v66, v88
	v_fma_f32 v88, v66, v88, v66
	v_mul_f32_e32 v88, 0xbfcc422a, v88
	v_mul_f32_e32 v88, 0x3fb8aa3b, v88
	v_exp_f32_e32 v88, v88
	v_cvt_pk_bf16_f32 v83, v84, v85
	s_nop 0
	v_add_f32_e32 v88, 1.0, v88
	v_rcp_f32_e32 v89, v88
	s_nop 0
	v_mul_f32_e32 v88, v66, v89
	v_mul_f32_e32 v89, 0x3d372713, v67
	v_mul_f32_e32 v89, v67, v89
	v_fma_f32 v89, v67, v89, v67
	v_mul_f32_e32 v89, 0xbfcc422a, v89
	v_mul_f32_e32 v89, 0x3fb8aa3b, v89
	v_exp_f32_e32 v89, v89
	s_nop 0
	v_add_f32_e32 v89, 1.0, v89
	v_rcp_f32_e32 v93, v89
	s_nop 0
	v_mul_f32_e32 v89, v67, v93
	v_mul_f32_e32 v93, 0x3d372713, v68
	v_mul_f32_e32 v93, v68, v93
	v_fma_f32 v93, v68, v93, v68
	v_mul_f32_e32 v93, 0xbfcc422a, v93
	v_mul_f32_e32 v93, 0x3fb8aa3b, v93
	v_exp_f32_e32 v93, v93
	v_cvt_pk_bf16_f32 v84, v88, v89
	v_lshl_add_u64 v[88:89], v[170:171], 0, s[42:43]
	v_readlane_b32 s43, v255, 41
	v_add_f32_e32 v93, 1.0, v93
	v_lshl_add_u64 v[86:87], v[88:89], 1, v[86:87]
	v_rcp_f32_e32 v94, v93
	s_nop 0
	v_mul_f32_e32 v93, v68, v94
	v_mul_f32_e32 v94, 0x3d372713, v69
	v_mul_f32_e32 v94, v69, v94
	v_fma_f32 v94, v69, v94, v69
	v_mul_f32_e32 v94, 0xbfcc422a, v94
	v_mul_f32_e32 v94, 0x3fb8aa3b, v94
	v_exp_f32_e32 v94, v94
	s_nop 0
	v_add_f32_e32 v94, 1.0, v94
	v_rcp_f32_e32 v95, v94
	s_nop 0
	v_mul_f32_e32 v94, v69, v95
	v_cvt_pk_bf16_f32 v85, v93, v94
	global_store_dwordx4 v[86:87], v[82:85], off offset:256

.LBB0_475:
	s_addk_i32 s64, 0x80
	v_or_b32_e32 v82, s64, v155
	v_bitop3_b32 v87, s64, v240, v155 bitop3:0xc8
	v_cmp_gt_i32_e64 s[8:9], s76, v82
	v_cmp_lt_i32_e64 s[10:11], s79, v82
	s_ashr_i32 s26, s64, 13
	v_cndmask_b32_e64 v86, v177, v87, s[8:9]
	s_and_b64 vcc, exec, s[6:7]
	s_mov_b64 s[12:13], -1
	s_cbranch_vccnz .LBB0_534
	v_add_u32_e32 v16, 0xffffc000, v82
	s_andn2_b64 vcc, exec, s[86:87]
	s_cbranch_vccnz .LBB0_506
	v_ashrrev_i32_e32 v83, 31, v82
	v_mov_b64_e32 v[66:67], s[14:15]
	s_movk_i32 s12, 0x60
	v_mad_i64_i32 v[72:73], s[12:13], v82, s12, v[66:67]
	v_lshlrev_b64 v[66:67], 10, v[82:83]
	v_lshl_add_u64 v[70:71], s[50:51], 0, v[66:67]
	v_cndmask_b32_e64 v66, 0, 1, s[44:45]
	v_cmp_ne_u32_e64 s[12:13], 1, v66
	s_andn2_b64 vcc, exec, s[44:45]
	s_mov_b64 s[52:53], -1
	s_cbranch_vccnz .LBB0_493
	s_andn2_b64 vcc, exec, s[46:47]
	s_cbranch_vccnz .LBB0_482
	s_movk_i32 s27, 0x918
	v_cmp_gt_i32_e32 vcc, s27, v170
	s_and_saveexec_b64 s[52:53], vcc
	s_cbranch_execz .LBB0_481
	v_mul_f32_e32 v68, 0xbfb8aa3b, v64
	v_mul_f32_e32 v69, 0xbfb8aa3b, v65
	v_exp_f32_e32 v68, v68
	v_exp_f32_e32 v69, v69
	v_mul_f32_e32 v66, 0xbfb8aa3b, v62
	v_mul_f32_e32 v67, 0xbfb8aa3b, v63
	v_exp_f32_e32 v66, v66
	v_pk_add_f32 v[68:69], v[68:69], 1.0 op_sel_hi:[1,0]
	v_exp_f32_e32 v67, v67
	s_nop 0
	v_pk_add_f32 v[66:67], v[66:67], 1.0 op_sel_hi:[1,0]
	v_mov_b32_e32 v171, v17
	v_lshl_add_u64 v[74:75], v[170:171], 2, v[72:73]
	v_rcp_f32_e32 v69, v69
	v_rcp_f32_e32 v68, v68
	s_nop 0
	v_rcp_f32_e32 v67, v67
	s_nop 0
	v_mul_f32_e32 v78, 0xbfb8aa3b, v60
	v_mul_f32_e32 v79, 0xbfb8aa3b, v61
	v_exp_f32_e32 v78, v78
	v_exp_f32_e32 v79, v79
	v_rcp_f32_e32 v66, v66
	v_mul_f32_e32 v76, 0xbfb8aa3b, v58
	v_mul_f32_e32 v77, 0xbfb8aa3b, v59
	v_pk_add_f32 v[78:79], v[78:79], 1.0 op_sel_hi:[1,0]
	v_exp_f32_e32 v76, v76
	v_exp_f32_e32 v77, v77
	v_rcp_f32_e32 v79, v79
	v_pk_add_f32 v[76:77], v[76:77], 1.0 op_sel_hi:[1,0]
	v_rcp_f32_e32 v78, v78
	v_rcp_f32_e32 v77, v77
	s_nop 0
	v_add_co_u32_e32 v74, vcc, 0x138fd000, v74
	v_rcp_f32_e32 v76, v76
	s_nop 0
	v_addc_co_u32_e32 v75, vcc, 0, v75, vcc
	global_store_dwordx4 v[74:75], v[66:69], off offset:3072
	global_store_dwordx4 v[74:75], v[76:79], off offset:3088

.LBB0_486:
	s_andn2_b64 vcc, exec, s[46:47]
	s_cbranch_vccnz .LBB0_490
	v_or_b32_e32 v66, 0x80, v170
	s_movk_i32 s12, 0x918
	v_cmp_gt_i32_e32 vcc, s12, v66
	s_and_saveexec_b64 s[12:13], vcc
	s_cbranch_execz .LBB0_489
	v_mul_f32_e32 v68, 0xbfb8aa3b, v56
	v_mul_f32_e32 v69, 0xbfb8aa3b, v57
	v_exp_f32_e32 v68, v68
	v_exp_f32_e32 v69, v69
	v_mul_f32_e32 v66, 0xbfb8aa3b, v54
	v_mul_f32_e32 v67, 0xbfb8aa3b, v55
	v_exp_f32_e32 v66, v66
	v_pk_add_f32 v[68:69], v[68:69], 1.0 op_sel_hi:[1,0]
	v_exp_f32_e32 v67, v67
	s_nop 0
	v_pk_add_f32 v[66:67], v[66:67], 1.0 op_sel_hi:[1,0]
	v_mov_b32_e32 v171, v17
	v_lshl_add_u64 v[72:73], v[170:171], 2, v[72:73]
	v_rcp_f32_e32 v69, v69
	v_rcp_f32_e32 v68, v68
	s_nop 0
	v_rcp_f32_e32 v67, v67
	s_nop 0
	v_rcp_f32_e32 v66, v66
	s_nop 0
	v_mul_f32_e32 v77, 0xbfb8aa3b, v50
	v_exp_f32_e32 v78, v77
	v_mul_f32_e32 v77, 0xbfb8aa3b, v51
	v_exp_f32_e32 v79, v77
	v_mul_f32_e32 v77, 0xbfb8aa3b, v52
	v_exp_f32_e32 v80, v77
	v_mul_f32_e32 v77, 0xbfb8aa3b, v53
	v_exp_f32_e32 v81, v77
	v_pk_add_f32 v[78:79], v[78:79], 1.0 op_sel_hi:[1,0]
	v_pk_add_f32 v[80:81], v[80:81], 1.0 op_sel_hi:[1,0]
	s_nop 0
	v_rcp_f32_e32 v81, v81
	s_nop 0
	v_rcp_f32_e32 v80, v80
	s_nop 0
	v_rcp_f32_e32 v79, v79
	s_nop 0
	v_add_co_u32_e32 v72, vcc, 0x138fd000, v72
	v_rcp_f32_e32 v78, v78
	s_nop 0
	v_addc_co_u32_e32 v73, vcc, 0, v73, vcc
	global_store_dwordx4 v[72:73], v[66:69], off offset:3584
	global_store_dwordx4 v[72:73], v[78:81], off offset:3600

.LBB0_490:
	s_andn2_b64 vcc, exec, s[12:13]
	s_cbranch_vccnz .LBB0_492
	v_mul_f32_e32 v66, 0x3d372713, v54
	v_mul_f32_e32 v66, v54, v66
	v_fma_f32 v66, v54, v66, v54
	v_mul_f32_e32 v66, 0xbfcc422a, v66
	v_mul_f32_e32 v66, 0x3fb8aa3b, v66
	v_exp_f32_e32 v66, v66
	s_ashr_i32 s43, s42, 31
	v_ashrrev_i32_e32 v171, 31, v170
	v_add_f32_e32 v66, 1.0, v66
	v_rcp_f32_e32 v67, v66
	s_nop 0
	v_mul_f32_e32 v66, v54, v67
	v_mul_f32_e32 v67, 0x3d372713, v55
	v_mul_f32_e32 v67, v55, v67
	v_fma_f32 v67, v55, v67, v55
	v_mul_f32_e32 v67, 0xbfcc422a, v67
	v_mul_f32_e32 v67, 0x3fb8aa3b, v67
	v_exp_f32_e32 v67, v67
	s_nop 0
	v_add_f32_e32 v67, 1.0, v67
	v_rcp_f32_e32 v68, v67
	s_nop 0
	v_mul_f32_e32 v67, v55, v68
	v_mul_f32_e32 v68, 0x3d372713, v56
	v_mul_f32_e32 v68, v56, v68
	v_fma_f32 v68, v56, v68, v56
	v_mul_f32_e32 v68, 0xbfcc422a, v68
	v_mul_f32_e32 v68, 0x3fb8aa3b, v68
	v_exp_f32_e32 v68, v68
	v_cvt_pk_bf16_f32 v66, v66, v67
	s_nop 0
	v_add_f32_e32 v68, 1.0, v68
	v_rcp_f32_e32 v69, v68
	s_nop 0
	v_mul_f32_e32 v68, v56, v69
	v_mul_f32_e32 v69, 0x3d372713, v57
	v_mul_f32_e32 v69, v57, v69
	v_fma_f32 v69, v57, v69, v57
	v_mul_f32_e32 v69, 0xbfcc422a, v69
	v_mul_f32_e32 v69, 0x3fb8aa3b, v69
	v_exp_f32_e32 v69, v69
	s_nop 0
	v_add_f32_e32 v69, 1.0, v69
	v_rcp_f32_e32 v72, v69
	s_nop 0
	v_mul_f32_e32 v69, v57, v72
	v_mul_f32_e32 v72, 0x3d372713, v50
	v_mul_f32_e32 v72, v50, v72
	v_fma_f32 v72, v50, v72, v50
	v_mul_f32_e32 v72, 0xbfcc422a, v72
	v_mul_f32_e32 v72, 0x3fb8aa3b, v72
	v_exp_f32_e32 v72, v72
	v_cvt_pk_bf16_f32 v67, v68, v69
	s_nop 0
	v_add_f32_e32 v72, 1.0, v72
	v_rcp_f32_e32 v73, v72
	s_nop 0
	v_mul_f32_e32 v72, v50, v73
	v_mul_f32_e32 v73, 0x3d372713, v51
	v_mul_f32_e32 v73, v51, v73
	v_fma_f32 v73, v51, v73, v51
	v_mul_f32_e32 v73, 0xbfcc422a, v73
	v_mul_f32_e32 v73, 0x3fb8aa3b, v73
	v_exp_f32_e32 v73, v73
	s_nop 0
	v_add_f32_e32 v73, 1.0, v73
	v_rcp_f32_e32 v77, v73
	s_nop 0
	v_mul_f32_e32 v73, v51, v77
	v_mul_f32_e32 v77, 0x3d372713, v52
	v_mul_f32_e32 v77, v52, v77
	v_fma_f32 v77, v52, v77, v52
	v_mul_f32_e32 v77, 0xbfcc422a, v77
	v_mul_f32_e32 v77, 0x3fb8aa3b, v77
	v_exp_f32_e32 v77, v77
	v_cvt_pk_bf16_f32 v68, v72, v73
	v_lshl_add_u64 v[72:73], v[170:171], 0, s[42:43]
	v_readlane_b32 s43, v255, 41
	v_add_f32_e32 v77, 1.0, v77
	v_lshl_add_u64 v[70:71], v[72:73], 1, v[70:71]
	v_rcp_f32_e32 v78, v77
	s_nop 0
	v_mul_f32_e32 v77, v52, v78
	v_mul_f32_e32 v78, 0x3d372713, v53
	v_mul_f32_e32 v78, v53, v78
	v_fma_f32 v78, v53, v78, v53
	v_mul_f32_e32 v78, 0xbfcc422a, v78
	v_mul_f32_e32 v78, 0x3fb8aa3b, v78
	v_exp_f32_e32 v78, v78
	s_nop 0
	v_add_f32_e32 v78, 1.0, v78
	v_rcp_f32_e32 v79, v78
	s_nop 0
	v_mul_f32_e32 v78, v53, v79
	v_cvt_pk_bf16_f32 v69, v77, v78
	global_store_dwordx4 v[70:71], v[66:69], off offset:256

.LBB0_536:
	v_or_b32_e32 v66, s64, v185
	v_bitop3_b32 v71, s64, v241, v185 bitop3:0xc8
	v_cmp_gt_i32_e64 s[8:9], s76, v66
	v_cmp_lt_i32_e64 s[10:11], s79, v66
	s_and_b64 vcc, exec, s[6:7]
	v_cndmask_b32_e64 v70, v177, v71, s[8:9]
	s_mov_b64 s[12:13], -1
	s_cbranch_vccnz .LBB0_595
	v_add_u32_e32 v16, 0xffffc000, v66
	s_andn2_b64 vcc, exec, s[86:87]
	s_cbranch_vccnz .LBB0_567
	v_ashrrev_i32_e32 v67, 31, v66
	v_mov_b64_e32 v[50:51], s[14:15]
	s_movk_i32 s12, 0x60
	v_mad_i64_i32 v[56:57], s[12:13], v66, s12, v[50:51]
	v_lshlrev_b64 v[50:51], 10, v[66:67]
	v_lshl_add_u64 v[54:55], s[50:51], 0, v[50:51]
	v_cndmask_b32_e64 v50, 0, 1, s[44:45]
	v_cmp_ne_u32_e64 s[12:13], 1, v50
	s_andn2_b64 vcc, exec, s[44:45]
	s_mov_b64 s[52:53], -1
	s_cbranch_vccnz .LBB0_554
	s_andn2_b64 vcc, exec, s[46:47]
	s_cbranch_vccnz .LBB0_543
	s_movk_i32 s27, 0x918
	v_cmp_gt_i32_e32 vcc, s27, v170
	s_and_saveexec_b64 s[52:53], vcc
	s_cbranch_execz .LBB0_542
	v_mul_f32_e32 v52, 0xbfb8aa3b, v48
	v_mul_f32_e32 v53, 0xbfb8aa3b, v49
	v_exp_f32_e32 v52, v52
	v_exp_f32_e32 v53, v53
	v_mul_f32_e32 v50, 0xbfb8aa3b, v46
	v_mul_f32_e32 v51, 0xbfb8aa3b, v47
	v_exp_f32_e32 v50, v50
	v_pk_add_f32 v[52:53], v[52:53], 1.0 op_sel_hi:[1,0]
	v_exp_f32_e32 v51, v51
	s_nop 0
	v_pk_add_f32 v[50:51], v[50:51], 1.0 op_sel_hi:[1,0]
	v_mov_b32_e32 v171, v17
	v_lshl_add_u64 v[58:59], v[170:171], 2, v[56:57]
	v_rcp_f32_e32 v53, v53
	v_rcp_f32_e32 v52, v52
	s_nop 0
	v_rcp_f32_e32 v51, v51
	s_nop 0
	v_mul_f32_e32 v62, 0xbfb8aa3b, v44
	v_mul_f32_e32 v63, 0xbfb8aa3b, v45
	v_exp_f32_e32 v62, v62
	v_exp_f32_e32 v63, v63
	v_rcp_f32_e32 v50, v50
	v_mul_f32_e32 v60, 0xbfb8aa3b, v42
	v_mul_f32_e32 v61, 0xbfb8aa3b, v43
	v_pk_add_f32 v[62:63], v[62:63], 1.0 op_sel_hi:[1,0]
	v_exp_f32_e32 v60, v60
	v_exp_f32_e32 v61, v61
	v_rcp_f32_e32 v63, v63
	v_pk_add_f32 v[60:61], v[60:61], 1.0 op_sel_hi:[1,0]
	v_rcp_f32_e32 v62, v62
	v_rcp_f32_e32 v61, v61
	s_nop 0
	v_add_co_u32_e32 v58, vcc, 0x138fd000, v58
	v_rcp_f32_e32 v60, v60
	s_nop 0
	v_addc_co_u32_e32 v59, vcc, 0, v59, vcc
	global_store_dwordx4 v[58:59], v[50:53], off offset:3072
	global_store_dwordx4 v[58:59], v[60:63], off offset:3088

.LBB0_547:
	s_andn2_b64 vcc, exec, s[46:47]
	s_cbranch_vccnz .LBB0_551
	v_or_b32_e32 v50, 0x80, v170
	s_movk_i32 s12, 0x918
	v_cmp_gt_i32_e32 vcc, s12, v50
	s_and_saveexec_b64 s[12:13], vcc
	s_cbranch_execz .LBB0_550
	v_mul_f32_e32 v52, 0xbfb8aa3b, v40
	v_mul_f32_e32 v53, 0xbfb8aa3b, v41
	v_exp_f32_e32 v52, v52
	v_exp_f32_e32 v53, v53
	v_mul_f32_e32 v50, 0xbfb8aa3b, v38
	v_mul_f32_e32 v51, 0xbfb8aa3b, v39
	v_exp_f32_e32 v50, v50
	v_pk_add_f32 v[52:53], v[52:53], 1.0 op_sel_hi:[1,0]
	v_exp_f32_e32 v51, v51
	s_nop 0
	v_pk_add_f32 v[50:51], v[50:51], 1.0 op_sel_hi:[1,0]
	v_mov_b32_e32 v171, v17
	v_lshl_add_u64 v[56:57], v[170:171], 2, v[56:57]
	v_rcp_f32_e32 v53, v53
	v_rcp_f32_e32 v52, v52
	s_nop 0
	v_rcp_f32_e32 v51, v51
	s_nop 0
	v_rcp_f32_e32 v50, v50
	s_nop 0
	v_mul_f32_e32 v61, 0xbfb8aa3b, v34
	v_exp_f32_e32 v62, v61
	v_mul_f32_e32 v61, 0xbfb8aa3b, v35
	v_exp_f32_e32 v63, v61
	v_mul_f32_e32 v61, 0xbfb8aa3b, v36
	v_exp_f32_e32 v64, v61
	v_mul_f32_e32 v61, 0xbfb8aa3b, v37
	v_exp_f32_e32 v65, v61
	v_pk_add_f32 v[62:63], v[62:63], 1.0 op_sel_hi:[1,0]
	v_pk_add_f32 v[64:65], v[64:65], 1.0 op_sel_hi:[1,0]
	s_nop 0
	v_rcp_f32_e32 v65, v65
	s_nop 0
	v_rcp_f32_e32 v64, v64
	s_nop 0
	v_rcp_f32_e32 v63, v63
	s_nop 0
	v_add_co_u32_e32 v56, vcc, 0x138fd000, v56
	v_rcp_f32_e32 v62, v62
	s_nop 0
	v_addc_co_u32_e32 v57, vcc, 0, v57, vcc
	global_store_dwordx4 v[56:57], v[50:53], off offset:3584
	global_store_dwordx4 v[56:57], v[62:65], off offset:3600

.LBB0_551:
	s_andn2_b64 vcc, exec, s[12:13]
	s_cbranch_vccnz .LBB0_553
	v_mul_f32_e32 v50, 0x3d372713, v38
	v_mul_f32_e32 v50, v38, v50
	v_fma_f32 v50, v38, v50, v38
	v_mul_f32_e32 v50, 0xbfcc422a, v50
	v_mul_f32_e32 v50, 0x3fb8aa3b, v50
	v_exp_f32_e32 v50, v50
	s_ashr_i32 s43, s42, 31
	v_ashrrev_i32_e32 v171, 31, v170
	v_add_f32_e32 v50, 1.0, v50
	v_rcp_f32_e32 v51, v50
	s_nop 0
	v_mul_f32_e32 v50, v38, v51
	v_mul_f32_e32 v51, 0x3d372713, v39
	v_mul_f32_e32 v51, v39, v51
	v_fma_f32 v51, v39, v51, v39
	v_mul_f32_e32 v51, 0xbfcc422a, v51
	v_mul_f32_e32 v51, 0x3fb8aa3b, v51
	v_exp_f32_e32 v51, v51
	s_nop 0
	v_add_f32_e32 v51, 1.0, v51
	v_rcp_f32_e32 v52, v51
	s_nop 0
	v_mul_f32_e32 v51, v39, v52
	v_mul_f32_e32 v52, 0x3d372713, v40
	v_mul_f32_e32 v52, v40, v52
	v_fma_f32 v52, v40, v52, v40
	v_mul_f32_e32 v52, 0xbfcc422a, v52
	v_mul_f32_e32 v52, 0x3fb8aa3b, v52
	v_exp_f32_e32 v52, v52
	v_cvt_pk_bf16_f32 v50, v50, v51
	s_nop 0
	v_add_f32_e32 v52, 1.0, v52
	v_rcp_f32_e32 v53, v52
	s_nop 0
	v_mul_f32_e32 v52, v40, v53
	v_mul_f32_e32 v53, 0x3d372713, v41
	v_mul_f32_e32 v53, v41, v53
	v_fma_f32 v53, v41, v53, v41
	v_mul_f32_e32 v53, 0xbfcc422a, v53
	v_mul_f32_e32 v53, 0x3fb8aa3b, v53
	v_exp_f32_e32 v53, v53
	s_nop 0
	v_add_f32_e32 v53, 1.0, v53
	v_rcp_f32_e32 v56, v53
	s_nop 0
	v_mul_f32_e32 v53, v41, v56
	v_mul_f32_e32 v56, 0x3d372713, v34
	v_mul_f32_e32 v56, v34, v56
	v_fma_f32 v56, v34, v56, v34
	v_mul_f32_e32 v56, 0xbfcc422a, v56
	v_mul_f32_e32 v56, 0x3fb8aa3b, v56
	v_exp_f32_e32 v56, v56
	v_cvt_pk_bf16_f32 v51, v52, v53
	s_nop 0
	v_add_f32_e32 v56, 1.0, v56
	v_rcp_f32_e32 v57, v56
	s_nop 0
	v_mul_f32_e32 v56, v34, v57
	v_mul_f32_e32 v57, 0x3d372713, v35
	v_mul_f32_e32 v57, v35, v57
	v_fma_f32 v57, v35, v57, v35
	v_mul_f32_e32 v57, 0xbfcc422a, v57
	v_mul_f32_e32 v57, 0x3fb8aa3b, v57
	v_exp_f32_e32 v57, v57
	s_nop 0
	v_add_f32_e32 v57, 1.0, v57
	v_rcp_f32_e32 v61, v57
	s_nop 0
	v_mul_f32_e32 v57, v35, v61
	v_mul_f32_e32 v61, 0x3d372713, v36
	v_mul_f32_e32 v61, v36, v61
	v_fma_f32 v61, v36, v61, v36
	v_mul_f32_e32 v61, 0xbfcc422a, v61
	v_mul_f32_e32 v61, 0x3fb8aa3b, v61
	v_exp_f32_e32 v61, v61
	v_cvt_pk_bf16_f32 v52, v56, v57
	v_lshl_add_u64 v[56:57], v[170:171], 0, s[42:43]
	v_readlane_b32 s43, v255, 41
	v_add_f32_e32 v61, 1.0, v61
	v_lshl_add_u64 v[54:55], v[56:57], 1, v[54:55]
	v_rcp_f32_e32 v62, v61
	s_nop 0
	v_mul_f32_e32 v61, v36, v62
	v_mul_f32_e32 v62, 0x3d372713, v37
	v_mul_f32_e32 v62, v37, v62
	v_fma_f32 v62, v37, v62, v37
	v_mul_f32_e32 v62, 0xbfcc422a, v62
	v_mul_f32_e32 v62, 0x3fb8aa3b, v62
	v_exp_f32_e32 v62, v62
	s_nop 0
	v_add_f32_e32 v62, 1.0, v62
	v_rcp_f32_e32 v63, v62
	s_nop 0
	v_mul_f32_e32 v62, v37, v63
	v_cvt_pk_bf16_f32 v53, v61, v62
	global_store_dwordx4 v[54:55], v[50:53], off offset:256

.LBB0_597:
	v_or_b32_e32 v50, s64, v186
	v_bitop3_b32 v55, s64, v242, v186 bitop3:0xc8
	v_cmp_gt_i32_e64 s[8:9], s76, v50
	v_cmp_lt_i32_e64 s[10:11], s79, v50
	s_and_b64 vcc, exec, s[6:7]
	v_cndmask_b32_e64 v54, v177, v55, s[8:9]
	s_mov_b64 s[12:13], -1
	s_cbranch_vccnz .LBB0_656
	v_add_u32_e32 v16, 0xffffc000, v50
	s_andn2_b64 vcc, exec, s[86:87]
	s_cbranch_vccnz .LBB0_628
	v_ashrrev_i32_e32 v51, 31, v50
	v_mov_b64_e32 v[34:35], s[14:15]
	s_movk_i32 s12, 0x60
	v_mad_i64_i32 v[40:41], s[12:13], v50, s12, v[34:35]
	v_lshlrev_b64 v[34:35], 10, v[50:51]
	v_lshl_add_u64 v[38:39], s[50:51], 0, v[34:35]
	v_cndmask_b32_e64 v34, 0, 1, s[44:45]
	v_cmp_ne_u32_e64 s[12:13], 1, v34
	s_andn2_b64 vcc, exec, s[44:45]
	s_mov_b64 s[52:53], -1
	s_cbranch_vccnz .LBB0_615
	s_andn2_b64 vcc, exec, s[46:47]
	s_cbranch_vccnz .LBB0_604
	s_movk_i32 s27, 0x918
	v_cmp_gt_i32_e32 vcc, s27, v170
	s_and_saveexec_b64 s[52:53], vcc
	s_cbranch_execz .LBB0_603
	v_mul_f32_e32 v36, 0xbfb8aa3b, v32
	v_mul_f32_e32 v37, 0xbfb8aa3b, v33
	v_exp_f32_e32 v36, v36
	v_exp_f32_e32 v37, v37
	v_mul_f32_e32 v34, 0xbfb8aa3b, v30
	v_mul_f32_e32 v35, 0xbfb8aa3b, v31
	v_exp_f32_e32 v34, v34
	v_pk_add_f32 v[36:37], v[36:37], 1.0 op_sel_hi:[1,0]
	v_exp_f32_e32 v35, v35
	s_nop 0
	v_pk_add_f32 v[34:35], v[34:35], 1.0 op_sel_hi:[1,0]
	v_mov_b32_e32 v171, v17
	v_lshl_add_u64 v[42:43], v[170:171], 2, v[40:41]
	v_rcp_f32_e32 v37, v37
	v_rcp_f32_e32 v36, v36
	s_nop 0
	v_rcp_f32_e32 v35, v35
	s_nop 0
	v_mul_f32_e32 v46, 0xbfb8aa3b, v28
	v_mul_f32_e32 v47, 0xbfb8aa3b, v29
	v_exp_f32_e32 v46, v46
	v_exp_f32_e32 v47, v47
	v_rcp_f32_e32 v34, v34
	v_mul_f32_e32 v44, 0xbfb8aa3b, v26
	v_mul_f32_e32 v45, 0xbfb8aa3b, v27
	v_pk_add_f32 v[46:47], v[46:47], 1.0 op_sel_hi:[1,0]
	v_exp_f32_e32 v44, v44
	v_exp_f32_e32 v45, v45
	v_rcp_f32_e32 v47, v47
	v_pk_add_f32 v[44:45], v[44:45], 1.0 op_sel_hi:[1,0]
	v_rcp_f32_e32 v46, v46
	v_rcp_f32_e32 v45, v45
	s_nop 0
	v_add_co_u32_e32 v42, vcc, 0x138fd000, v42
	v_rcp_f32_e32 v44, v44
	s_nop 0
	v_addc_co_u32_e32 v43, vcc, 0, v43, vcc
	global_store_dwordx4 v[42:43], v[34:37], off offset:3072
	global_store_dwordx4 v[42:43], v[44:47], off offset:3088

.LBB0_608:
	s_andn2_b64 vcc, exec, s[46:47]
	s_cbranch_vccnz .LBB0_612
	v_or_b32_e32 v34, 0x80, v170
	s_movk_i32 s12, 0x918
	v_cmp_gt_i32_e32 vcc, s12, v34
	s_and_saveexec_b64 s[12:13], vcc
	s_cbranch_execz .LBB0_611
	v_mul_f32_e32 v36, 0xbfb8aa3b, v24
	v_mul_f32_e32 v37, 0xbfb8aa3b, v25
	v_exp_f32_e32 v36, v36
	v_exp_f32_e32 v37, v37
	v_mul_f32_e32 v34, 0xbfb8aa3b, v22
	v_mul_f32_e32 v35, 0xbfb8aa3b, v23
	v_exp_f32_e32 v34, v34
	v_pk_add_f32 v[36:37], v[36:37], 1.0 op_sel_hi:[1,0]
	v_exp_f32_e32 v35, v35
	s_nop 0
	v_pk_add_f32 v[34:35], v[34:35], 1.0 op_sel_hi:[1,0]
	v_mov_b32_e32 v171, v17
	v_lshl_add_u64 v[40:41], v[170:171], 2, v[40:41]
	v_rcp_f32_e32 v37, v37
	v_rcp_f32_e32 v36, v36
	s_nop 0
	v_rcp_f32_e32 v35, v35
	s_nop 0
	v_rcp_f32_e32 v34, v34
	s_nop 0
	v_mul_f32_e32 v45, 0xbfb8aa3b, v18
	v_exp_f32_e32 v46, v45
	v_mul_f32_e32 v45, 0xbfb8aa3b, v19
	v_exp_f32_e32 v47, v45
	v_mul_f32_e32 v45, 0xbfb8aa3b, v20
	v_exp_f32_e32 v48, v45
	v_mul_f32_e32 v45, 0xbfb8aa3b, v21
	v_exp_f32_e32 v49, v45
	v_pk_add_f32 v[46:47], v[46:47], 1.0 op_sel_hi:[1,0]
	v_pk_add_f32 v[48:49], v[48:49], 1.0 op_sel_hi:[1,0]
	s_nop 0
	v_rcp_f32_e32 v49, v49
	s_nop 0
	v_rcp_f32_e32 v48, v48
	s_nop 0
	v_rcp_f32_e32 v47, v47
	s_nop 0
	v_add_co_u32_e32 v40, vcc, 0x138fd000, v40
	v_rcp_f32_e32 v46, v46
	s_nop 0
	v_addc_co_u32_e32 v41, vcc, 0, v41, vcc
	global_store_dwordx4 v[40:41], v[34:37], off offset:3584
	global_store_dwordx4 v[40:41], v[46:49], off offset:3600

.LBB0_612:
	s_andn2_b64 vcc, exec, s[12:13]
	s_cbranch_vccnz .LBB0_614
	v_mul_f32_e32 v34, 0x3d372713, v22
	v_mul_f32_e32 v34, v22, v34
	v_fma_f32 v34, v22, v34, v22
	v_mul_f32_e32 v34, 0xbfcc422a, v34
	v_mul_f32_e32 v34, 0x3fb8aa3b, v34
	v_exp_f32_e32 v34, v34
	s_ashr_i32 s43, s42, 31
	v_ashrrev_i32_e32 v171, 31, v170
	v_add_f32_e32 v34, 1.0, v34
	v_rcp_f32_e32 v35, v34
	s_nop 0
	v_mul_f32_e32 v34, v22, v35
	v_mul_f32_e32 v35, 0x3d372713, v23
	v_mul_f32_e32 v35, v23, v35
	v_fma_f32 v35, v23, v35, v23
	v_mul_f32_e32 v35, 0xbfcc422a, v35
	v_mul_f32_e32 v35, 0x3fb8aa3b, v35
	v_exp_f32_e32 v35, v35
	s_nop 0
	v_add_f32_e32 v35, 1.0, v35
	v_rcp_f32_e32 v36, v35
	s_nop 0
	v_mul_f32_e32 v35, v23, v36
	v_mul_f32_e32 v36, 0x3d372713, v24
	v_mul_f32_e32 v36, v24, v36
	v_fma_f32 v36, v24, v36, v24
	v_mul_f32_e32 v36, 0xbfcc422a, v36
	v_mul_f32_e32 v36, 0x3fb8aa3b, v36
	v_exp_f32_e32 v36, v36
	v_cvt_pk_bf16_f32 v34, v34, v35
	s_nop 0
	v_add_f32_e32 v36, 1.0, v36
	v_rcp_f32_e32 v37, v36
	s_nop 0
	v_mul_f32_e32 v36, v24, v37
	v_mul_f32_e32 v37, 0x3d372713, v25
	v_mul_f32_e32 v37, v25, v37
	v_fma_f32 v37, v25, v37, v25
	v_mul_f32_e32 v37, 0xbfcc422a, v37
	v_mul_f32_e32 v37, 0x3fb8aa3b, v37
	v_exp_f32_e32 v37, v37
	s_nop 0
	v_add_f32_e32 v37, 1.0, v37
	v_rcp_f32_e32 v40, v37
	s_nop 0
	v_mul_f32_e32 v37, v25, v40
	v_mul_f32_e32 v40, 0x3d372713, v18
	v_mul_f32_e32 v40, v18, v40
	v_fma_f32 v40, v18, v40, v18
	v_mul_f32_e32 v40, 0xbfcc422a, v40
	v_mul_f32_e32 v40, 0x3fb8aa3b, v40
	v_exp_f32_e32 v40, v40
	v_cvt_pk_bf16_f32 v35, v36, v37
	s_nop 0
	v_add_f32_e32 v40, 1.0, v40
	v_rcp_f32_e32 v41, v40
	s_nop 0
	v_mul_f32_e32 v40, v18, v41
	v_mul_f32_e32 v41, 0x3d372713, v19
	v_mul_f32_e32 v41, v19, v41
	v_fma_f32 v41, v19, v41, v19
	v_mul_f32_e32 v41, 0xbfcc422a, v41
	v_mul_f32_e32 v41, 0x3fb8aa3b, v41
	v_exp_f32_e32 v41, v41
	s_nop 0
	v_add_f32_e32 v41, 1.0, v41
	v_rcp_f32_e32 v45, v41
	s_nop 0
	v_mul_f32_e32 v41, v19, v45
	v_mul_f32_e32 v45, 0x3d372713, v20
	v_mul_f32_e32 v45, v20, v45
	v_fma_f32 v45, v20, v45, v20
	v_mul_f32_e32 v45, 0xbfcc422a, v45
	v_mul_f32_e32 v45, 0x3fb8aa3b, v45
	v_exp_f32_e32 v45, v45
	v_cvt_pk_bf16_f32 v36, v40, v41
	v_lshl_add_u64 v[40:41], v[170:171], 0, s[42:43]
	v_readlane_b32 s43, v255, 41
	v_add_f32_e32 v45, 1.0, v45
	v_lshl_add_u64 v[38:39], v[40:41], 1, v[38:39]
	v_rcp_f32_e32 v46, v45
	s_nop 0
	v_mul_f32_e32 v45, v20, v46
	v_mul_f32_e32 v46, 0x3d372713, v21
	v_mul_f32_e32 v46, v21, v46
	v_fma_f32 v46, v21, v46, v21
	v_mul_f32_e32 v46, 0xbfcc422a, v46
	v_mul_f32_e32 v46, 0x3fb8aa3b, v46
	v_exp_f32_e32 v46, v46
	s_nop 0
	v_add_f32_e32 v46, 1.0, v46
	v_rcp_f32_e32 v47, v46
	s_nop 0
	v_mul_f32_e32 v46, v21, v47
	v_cvt_pk_bf16_f32 v37, v45, v46
	global_store_dwordx4 v[38:39], v[34:37], off offset:256

.LBB0_658:
	v_or_b32_e32 v34, s64, v187
	v_bitop3_b32 v39, s64, v243, v187 bitop3:0xc8
	v_cmp_gt_i32_e64 s[8:9], s76, v34
	v_cmp_lt_i32_e64 s[10:11], s79, v34
	s_and_b64 vcc, exec, s[6:7]
	v_cndmask_b32_e64 v38, v177, v39, s[8:9]
	s_mov_b64 s[6:7], -1
	s_cbranch_vccnz .LBB0_676
	v_add_u32_e32 v16, 0xffffc000, v34
	s_andn2_b64 vcc, exec, s[86:87]
	s_cbranch_vccnz .LBB0_691
	v_ashrrev_i32_e32 v35, 31, v34
	v_mov_b64_e32 v[18:19], s[14:15]
	s_movk_i32 s6, 0x60
	v_mad_i64_i32 v[24:25], s[6:7], v34, s6, v[18:19]
	v_lshlrev_b64 v[18:19], 10, v[34:35]
	v_lshl_add_u64 v[22:23], s[50:51], 0, v[18:19]
	v_cndmask_b32_e64 v18, 0, 1, s[44:45]
	v_cmp_ne_u32_e64 s[12:13], 1, v18
	v_cndmask_b32_e64 v18, 0, 1, s[46:47]
	s_mov_b64 s[50:51], -1
	s_andn2_b64 vcc, exec, s[44:45]
	v_cmp_ne_u32_e64 s[6:7], 1, v18
	s_cbranch_vccnz .LBB0_678
	s_and_b64 vcc, exec, s[6:7]
	s_mov_b64 s[44:45], -1
	s_cbranch_vccnz .LBB0_665
	s_movk_i32 s27, 0x918
	v_cmp_gt_i32_e32 vcc, s27, v170
	s_and_saveexec_b64 s[44:45], vcc
	s_cbranch_execz .LBB0_664
	v_mul_f32_e32 v20, 0xbfb8aa3b, v14
	v_mul_f32_e32 v21, 0xbfb8aa3b, v15
	v_exp_f32_e32 v20, v20
	v_exp_f32_e32 v21, v21
	v_mul_f32_e32 v18, 0xbfb8aa3b, v12
	v_mul_f32_e32 v19, 0xbfb8aa3b, v13
	v_exp_f32_e32 v18, v18
	v_pk_add_f32 v[20:21], v[20:21], 1.0 op_sel_hi:[1,0]
	v_exp_f32_e32 v19, v19
	s_nop 0
	v_pk_add_f32 v[18:19], v[18:19], 1.0 op_sel_hi:[1,0]
	v_mov_b32_e32 v171, v17
	v_lshl_add_u64 v[26:27], v[170:171], 2, v[24:25]
	v_rcp_f32_e32 v21, v21
	v_rcp_f32_e32 v20, v20
	s_nop 0
	v_rcp_f32_e32 v19, v19
	s_nop 0
	v_mul_f32_e32 v30, 0xbfb8aa3b, v10
	v_mul_f32_e32 v31, 0xbfb8aa3b, v11
	v_exp_f32_e32 v30, v30
	v_exp_f32_e32 v31, v31
	v_rcp_f32_e32 v18, v18
	v_mul_f32_e32 v28, 0xbfb8aa3b, v8
	v_mul_f32_e32 v29, 0xbfb8aa3b, v9
	v_pk_add_f32 v[30:31], v[30:31], 1.0 op_sel_hi:[1,0]
	v_exp_f32_e32 v28, v28
	v_exp_f32_e32 v29, v29
	v_rcp_f32_e32 v31, v31
	v_pk_add_f32 v[28:29], v[28:29], 1.0 op_sel_hi:[1,0]
	v_rcp_f32_e32 v30, v30
	v_rcp_f32_e32 v29, v29
	s_nop 0
	v_add_co_u32_e32 v26, vcc, 0x138fd000, v26
	v_rcp_f32_e32 v28, v28
	s_nop 0
	v_addc_co_u32_e32 v27, vcc, 0, v27, vcc
	global_store_dwordx4 v[26:27], v[18:21], off offset:3072
	global_store_dwordx4 v[26:27], v[28:31], off offset:3088

.LBB0_669:
	s_and_b64 vcc, exec, s[6:7]
	s_mov_b64 s[6:7], -1
	s_cbranch_vccnz .LBB0_673
	v_or_b32_e32 v18, 0x80, v170
	s_movk_i32 s6, 0x918
	v_cmp_gt_i32_e32 vcc, s6, v18
	s_and_saveexec_b64 s[6:7], vcc
	s_cbranch_execz .LBB0_672
	v_mul_f32_e32 v20, 0xbfb8aa3b, v6
	v_mul_f32_e32 v21, 0xbfb8aa3b, v7
	v_exp_f32_e32 v20, v20
	v_exp_f32_e32 v21, v21
	v_mul_f32_e32 v18, 0xbfb8aa3b, v4
	v_mul_f32_e32 v19, 0xbfb8aa3b, v5
	v_exp_f32_e32 v18, v18
	v_pk_add_f32 v[20:21], v[20:21], 1.0 op_sel_hi:[1,0]
	v_exp_f32_e32 v19, v19
	s_nop 0
	v_pk_add_f32 v[18:19], v[18:19], 1.0 op_sel_hi:[1,0]
	v_mov_b32_e32 v171, v17
	v_lshl_add_u64 v[24:25], v[170:171], 2, v[24:25]
	v_rcp_f32_e32 v21, v21
	v_rcp_f32_e32 v20, v20
	s_nop 0
	v_rcp_f32_e32 v19, v19
	s_nop 0
	v_rcp_f32_e32 v18, v18
	s_nop 0
	v_mul_f32_e32 v29, 0xbfb8aa3b, v0
	v_exp_f32_e32 v30, v29
	v_mul_f32_e32 v29, 0xbfb8aa3b, v1
	v_exp_f32_e32 v31, v29
	v_mul_f32_e32 v29, 0xbfb8aa3b, v2
	v_exp_f32_e32 v32, v29
	v_mul_f32_e32 v29, 0xbfb8aa3b, v3
	v_exp_f32_e32 v33, v29
	v_pk_add_f32 v[30:31], v[30:31], 1.0 op_sel_hi:[1,0]
	v_pk_add_f32 v[32:33], v[32:33], 1.0 op_sel_hi:[1,0]
	s_nop 0
	v_rcp_f32_e32 v33, v33
	s_nop 0
	v_rcp_f32_e32 v32, v32
	s_nop 0
	v_rcp_f32_e32 v31, v31
	s_nop 0
	v_add_co_u32_e32 v24, vcc, 0x138fd000, v24
	v_rcp_f32_e32 v30, v30
	s_nop 0
	v_addc_co_u32_e32 v25, vcc, 0, v25, vcc
	global_store_dwordx4 v[24:25], v[18:21], off offset:3584
	global_store_dwordx4 v[24:25], v[30:33], off offset:3600

.LBB0_673:
	s_andn2_b64 vcc, exec, s[6:7]
	s_cbranch_vccnz .LBB0_675
	v_mul_f32_e32 v18, 0x3d372713, v4
	v_mul_f32_e32 v18, v4, v18
	v_fma_f32 v18, v4, v18, v4
	v_mul_f32_e32 v18, 0xbfcc422a, v18
	v_mul_f32_e32 v18, 0x3fb8aa3b, v18
	v_exp_f32_e32 v18, v18
	s_ashr_i32 s43, s42, 31
	v_ashrrev_i32_e32 v171, 31, v170
	v_add_f32_e32 v18, 1.0, v18
	v_rcp_f32_e32 v19, v18
	s_nop 0
	v_mul_f32_e32 v18, v4, v19
	v_mul_f32_e32 v19, 0x3d372713, v5
	v_mul_f32_e32 v19, v5, v19
	v_fma_f32 v19, v5, v19, v5
	v_mul_f32_e32 v19, 0xbfcc422a, v19
	v_mul_f32_e32 v19, 0x3fb8aa3b, v19
	v_exp_f32_e32 v19, v19
	s_nop 0
	v_add_f32_e32 v19, 1.0, v19
	v_rcp_f32_e32 v20, v19
	s_nop 0
	v_mul_f32_e32 v19, v5, v20
	v_mul_f32_e32 v20, 0x3d372713, v6
	v_mul_f32_e32 v20, v6, v20
	v_fma_f32 v20, v6, v20, v6
	v_mul_f32_e32 v20, 0xbfcc422a, v20
	v_mul_f32_e32 v20, 0x3fb8aa3b, v20
	v_exp_f32_e32 v20, v20
	v_cvt_pk_bf16_f32 v18, v18, v19
	s_nop 0
	v_add_f32_e32 v20, 1.0, v20
	v_rcp_f32_e32 v21, v20
	s_nop 0
	v_mul_f32_e32 v20, v6, v21
	v_mul_f32_e32 v21, 0x3d372713, v7
	v_mul_f32_e32 v21, v7, v21
	v_fma_f32 v21, v7, v21, v7
	v_mul_f32_e32 v21, 0xbfcc422a, v21
	v_mul_f32_e32 v21, 0x3fb8aa3b, v21
	v_exp_f32_e32 v21, v21
	s_nop 0
	v_add_f32_e32 v21, 1.0, v21
	v_rcp_f32_e32 v24, v21
	s_nop 0
	v_mul_f32_e32 v21, v7, v24
	v_mul_f32_e32 v24, 0x3d372713, v0
	v_mul_f32_e32 v24, v0, v24
	v_fma_f32 v24, v0, v24, v0
	v_mul_f32_e32 v24, 0xbfcc422a, v24
	v_mul_f32_e32 v24, 0x3fb8aa3b, v24
	v_exp_f32_e32 v24, v24
	v_cvt_pk_bf16_f32 v19, v20, v21
	s_nop 0
	v_add_f32_e32 v24, 1.0, v24
	v_rcp_f32_e32 v25, v24
	s_nop 0
	v_mul_f32_e32 v24, v0, v25
	v_mul_f32_e32 v25, 0x3d372713, v1
	v_mul_f32_e32 v25, v1, v25
	v_fma_f32 v25, v1, v25, v1
	v_mul_f32_e32 v25, 0xbfcc422a, v25
	v_mul_f32_e32 v25, 0x3fb8aa3b, v25
	v_exp_f32_e32 v25, v25
	s_nop 0
	v_add_f32_e32 v25, 1.0, v25
	v_rcp_f32_e32 v29, v25
	s_nop 0
	v_mul_f32_e32 v25, v1, v29
	v_mul_f32_e32 v29, 0x3d372713, v2
	v_mul_f32_e32 v29, v2, v29
	v_fma_f32 v29, v2, v29, v2
	v_mul_f32_e32 v29, 0xbfcc422a, v29
	v_mul_f32_e32 v29, 0x3fb8aa3b, v29
	v_exp_f32_e32 v29, v29
	v_cvt_pk_bf16_f32 v20, v24, v25
	v_lshl_add_u64 v[24:25], v[170:171], 0, s[42:43]
	v_readlane_b32 s43, v255, 41
	v_add_f32_e32 v29, 1.0, v29
	v_lshl_add_u64 v[22:23], v[24:25], 1, v[22:23]
	v_rcp_f32_e32 v30, v29
	s_nop 0
	v_mul_f32_e32 v29, v2, v30
	v_mul_f32_e32 v30, 0x3d372713, v3
	v_mul_f32_e32 v30, v3, v30
	v_fma_f32 v30, v3, v30, v3
	v_mul_f32_e32 v30, 0xbfcc422a, v30
	v_mul_f32_e32 v30, 0x3fb8aa3b, v30
	v_exp_f32_e32 v30, v30
	s_nop 0
	v_add_f32_e32 v30, 1.0, v30
	v_rcp_f32_e32 v31, v30
	s_nop 0
	v_mul_f32_e32 v30, v3, v31
	v_cvt_pk_bf16_f32 v21, v29, v30
	global_store_dwordx4 v[22:23], v[18:21], off offset:256

.LBB0_815:
	s_waitcnt lgkmcnt(0)
	global_load_dwordx4 v[8:11], v[0:1], off
	s_waitcnt vmcnt(0)
	v_lshlrev_b32_e32 v12, 16, v8
	v_and_b32_e32 v13, 0xffff0000, v8
	v_add_f32_e32 v8, 0, v12
	v_lshlrev_b32_e32 v14, 16, v9
	v_add_f32_e32 v8, v8, v13
	v_and_b32_e32 v9, 0xffff0000, v9
	v_add_f32_e32 v8, v8, v14
	v_lshlrev_b32_e32 v15, 16, v10
	v_add_f32_e32 v8, v8, v9
	v_and_b32_e32 v10, 0xffff0000, v10
	v_add_f32_e32 v8, v8, v15
	v_lshlrev_b32_e32 v16, 16, v11
	v_add_f32_e32 v8, v8, v10
	v_and_b32_e32 v11, 0xffff0000, v11
	v_add_f32_e32 v8, v8, v16
	v_add_f32_e32 v8, v8, v11
	ds_bpermute_b32 v18, v2, v8
	s_waitcnt lgkmcnt(0)
	v_add_f32_e32 v8, v8, v18
	ds_bpermute_b32 v18, v3, v8
	s_waitcnt lgkmcnt(0)
	v_add_f32_e32 v8, v8, v18
	ds_bpermute_b32 v18, v4, v8
	s_waitcnt lgkmcnt(0)
	v_add_f32_e32 v8, v8, v18
	ds_bpermute_b32 v18, v5, v8
	s_waitcnt lgkmcnt(0)
	v_add_f32_e32 v8, v8, v18
	ds_bpermute_b32 v18, v6, v8
	s_waitcnt lgkmcnt(0)
	v_add_f32_e32 v8, v8, v18
	ds_bpermute_b32 v18, v7, v8
	s_waitcnt lgkmcnt(0)
	v_add_f32_e32 v8, v8, v18
	v_fmac_f32_e32 v13, 0xbb000000, v8
	v_fmac_f32_e32 v12, 0xbb000000, v8
	v_mul_f32_e32 v13, v13, v13
	v_fmac_f32_e32 v14, 0xbb000000, v8
	v_fmac_f32_e32 v13, v12, v12
	v_fmac_f32_e32 v9, 0xbb000000, v8
	v_fmac_f32_e32 v13, v14, v14
	v_fmac_f32_e32 v15, 0xbb000000, v8
	v_fmac_f32_e32 v13, v9, v9
	v_fmac_f32_e32 v10, 0xbb000000, v8
	v_fmac_f32_e32 v13, v15, v15
	v_fmac_f32_e32 v16, 0xbb000000, v8
	v_fmac_f32_e32 v13, v10, v10
	v_fmac_f32_e32 v13, v16, v16
	v_fmac_f32_e32 v11, 0xbb000000, v8
	v_fmac_f32_e32 v13, v11, v11
	ds_bpermute_b32 v9, v2, v13
	s_waitcnt lgkmcnt(0)
	v_add_f32_e32 v9, v13, v9
	ds_bpermute_b32 v10, v3, v9
	s_waitcnt lgkmcnt(0)
	v_add_f32_e32 v9, v9, v10
	ds_bpermute_b32 v10, v4, v9
	s_waitcnt lgkmcnt(0)
	v_add_f32_e32 v9, v9, v10
	ds_bpermute_b32 v10, v5, v9
	s_waitcnt lgkmcnt(0)
	v_add_f32_e32 v9, v9, v10
	ds_bpermute_b32 v10, v6, v9
	s_waitcnt lgkmcnt(0)
	v_add_f32_e32 v9, v9, v10
	ds_bpermute_b32 v10, v7, v9
	s_and_saveexec_b64 s[42:43], s[4:5]
	s_cbranch_execz .LBB0_817
	s_waitcnt lgkmcnt(0)
	v_add_f32_e32 v9, v9, v10
	v_fmamk_f32 v9, v9, 0x3b000000, v238
	v_mul_f32_e32 v10, 0x4f800000, v9
	v_cmp_gt_f32_e32 vcc, s82, v9
	v_mul_f32_e32 v8, 0x3b000000, v8
	s_nop 0
	v_cndmask_b32_e32 v9, v9, v10, vcc
	v_sqrt_f32_e32 v10, v9
	s_nop 0
	v_add_u32_e32 v11, -1, v10
	v_fma_f32 v13, -v11, v10, v9
	v_add_u32_e32 v12, 1, v10
	v_cmp_ge_f32_e64 s[6:7], 0, v13
	s_nop 1
	v_cndmask_b32_e64 v11, v10, v11, s[6:7]
	v_fma_f32 v10, -v12, v10, v9
	v_cmp_lt_f32_e64 s[6:7], 0, v10
	s_nop 1
	v_cndmask_b32_e64 v10, v11, v12, s[6:7]
	v_mul_f32_e32 v11, 0x37800000, v10
	v_cndmask_b32_e32 v10, v10, v11, vcc
	v_cmp_class_f32_e32 vcc, v9, v239
	s_nop 1
	v_cndmask_b32_e32 v9, v10, v9, vcc
	s_add_i32 s6, s46, s47
	s_add_i32 s6, s6, 0x23480
	v_rcp_f32_e32 v9, v9
	v_mov_b32_e32 v10, s6
	ds_write_b64 v10, v[8:9]
.LBB0_817:
	s_or_b64 exec, exec, s[42:43]
	s_add_i32 s42, s37, s68
	s_ashr_i32 s43, s42, 31
	s_lshl_b64 s[6:7], s[42:43], 10
	v_lshl_add_u64 v[8:9], v[184:185], 0, s[6:7]
	s_waitcnt lgkmcnt(0)
	global_load_dwordx4 v[8:11], v[8:9], off
	s_waitcnt vmcnt(0)
	v_lshlrev_b32_e32 v12, 16, v8
	v_and_b32_e32 v13, 0xffff0000, v8
	v_add_f32_e32 v8, 0, v12
	v_lshlrev_b32_e32 v14, 16, v9
	v_add_f32_e32 v8, v8, v13
	v_and_b32_e32 v9, 0xffff0000, v9
	v_add_f32_e32 v8, v8, v14
	v_lshlrev_b32_e32 v15, 16, v10
	v_add_f32_e32 v8, v8, v9
	v_and_b32_e32 v10, 0xffff0000, v10
	v_add_f32_e32 v8, v8, v15
	v_lshlrev_b32_e32 v16, 16, v11
	v_add_f32_e32 v8, v8, v10
	v_and_b32_e32 v11, 0xffff0000, v11
	v_add_f32_e32 v8, v8, v16
	v_add_f32_e32 v8, v8, v11
	ds_bpermute_b32 v18, v2, v8
	s_waitcnt lgkmcnt(0)
	v_add_f32_e32 v8, v8, v18
	ds_bpermute_b32 v18, v3, v8
	s_waitcnt lgkmcnt(0)
	v_add_f32_e32 v8, v8, v18
	ds_bpermute_b32 v18, v4, v8
	s_waitcnt lgkmcnt(0)
	v_add_f32_e32 v8, v8, v18
	ds_bpermute_b32 v18, v5, v8
	s_waitcnt lgkmcnt(0)
	v_add_f32_e32 v8, v8, v18
	ds_bpermute_b32 v18, v6, v8
	s_waitcnt lgkmcnt(0)
	v_add_f32_e32 v8, v8, v18
	ds_bpermute_b32 v18, v7, v8
	s_waitcnt lgkmcnt(0)
	v_add_f32_e32 v8, v8, v18
	v_fmac_f32_e32 v13, 0xbb000000, v8
	v_fmac_f32_e32 v12, 0xbb000000, v8
	v_mul_f32_e32 v13, v13, v13
	v_fmac_f32_e32 v14, 0xbb000000, v8
	v_fmac_f32_e32 v13, v12, v12
	v_fmac_f32_e32 v9, 0xbb000000, v8
	v_fmac_f32_e32 v13, v14, v14
	v_fmac_f32_e32 v15, 0xbb000000, v8
	v_fmac_f32_e32 v13, v9, v9
	v_fmac_f32_e32 v10, 0xbb000000, v8
	v_fmac_f32_e32 v13, v15, v15
	v_fmac_f32_e32 v16, 0xbb000000, v8
	v_fmac_f32_e32 v13, v10, v10
	v_fmac_f32_e32 v13, v16, v16
	v_fmac_f32_e32 v11, 0xbb000000, v8
	v_fmac_f32_e32 v13, v11, v11
	ds_bpermute_b32 v9, v2, v13
	s_waitcnt lgkmcnt(0)
	v_add_f32_e32 v9, v13, v9
	ds_bpermute_b32 v10, v3, v9
	s_waitcnt lgkmcnt(0)
	v_add_f32_e32 v9, v9, v10
	ds_bpermute_b32 v10, v4, v9
	s_waitcnt lgkmcnt(0)
	v_add_f32_e32 v9, v9, v10
	ds_bpermute_b32 v10, v5, v9
	s_waitcnt lgkmcnt(0)
	v_add_f32_e32 v9, v9, v10
	ds_bpermute_b32 v10, v6, v9
	s_waitcnt lgkmcnt(0)
	v_add_f32_e32 v9, v9, v10
	ds_bpermute_b32 v10, v7, v9
	s_and_saveexec_b64 s[44:45], s[4:5]
	s_cbranch_execz .LBB0_819
	s_waitcnt lgkmcnt(0)
	v_add_f32_e32 v9, v9, v10
	v_fmamk_f32 v9, v9, 0x3b000000, v238
	v_mul_f32_e32 v10, 0x4f800000, v9
	v_cmp_gt_f32_e32 vcc, s82, v9
	v_mul_f32_e32 v8, 0x3b000000, v8
	s_nop 0
	v_cndmask_b32_e32 v9, v9, v10, vcc
	v_sqrt_f32_e32 v10, v9
	s_nop 0
	v_add_u32_e32 v11, -1, v10
	v_fma_f32 v13, -v11, v10, v9
	v_add_u32_e32 v12, 1, v10
	v_cmp_ge_f32_e64 s[6:7], 0, v13
	s_nop 1
	v_cndmask_b32_e64 v11, v10, v11, s[6:7]
	v_fma_f32 v10, -v12, v10, v9
	v_cmp_lt_f32_e64 s[6:7], 0, v10
	s_nop 1
	v_cndmask_b32_e64 v10, v11, v12, s[6:7]
	v_mul_f32_e32 v11, 0x37800000, v10
	v_cndmask_b32_e32 v10, v10, v11, vcc
	v_cmp_class_f32_e32 vcc, v9, v239
	s_nop 1
	v_cndmask_b32_e32 v9, v10, v9, vcc
	s_add_i32 s6, s46, s47
	s_add_i32 s6, s6, 0x23488
	v_rcp_f32_e32 v9, v9
	v_mov_b32_e32 v10, s6
	ds_write_b64 v10, v[8:9]
.LBB0_819:
	s_or_b64 exec, exec, s[44:45]
	s_add_i32 s6, s42, 1
	s_ashr_i32 s7, s6, 31
	s_lshl_b64 s[6:7], s[6:7], 10
	v_lshl_add_u64 v[8:9], v[184:185], 0, s[6:7]
	s_waitcnt lgkmcnt(0)
	global_load_dwordx4 v[8:11], v[8:9], off
	s_waitcnt vmcnt(0)
	v_lshlrev_b32_e32 v12, 16, v8
	v_and_b32_e32 v13, 0xffff0000, v8
	v_add_f32_e32 v8, 0, v12
	v_lshlrev_b32_e32 v14, 16, v9
	v_add_f32_e32 v8, v8, v13
	v_and_b32_e32 v9, 0xffff0000, v9
	v_add_f32_e32 v8, v8, v14
	v_lshlrev_b32_e32 v15, 16, v10
	v_add_f32_e32 v8, v8, v9
	v_and_b32_e32 v10, 0xffff0000, v10
	v_add_f32_e32 v8, v8, v15
	v_lshlrev_b32_e32 v16, 16, v11
	v_add_f32_e32 v8, v8, v10
	v_and_b32_e32 v11, 0xffff0000, v11
	v_add_f32_e32 v8, v8, v16
	v_add_f32_e32 v8, v8, v11
	ds_bpermute_b32 v18, v2, v8
	s_waitcnt lgkmcnt(0)
	v_add_f32_e32 v8, v8, v18
	ds_bpermute_b32 v18, v3, v8
	s_waitcnt lgkmcnt(0)
	v_add_f32_e32 v8, v8, v18
	ds_bpermute_b32 v18, v4, v8
	s_waitcnt lgkmcnt(0)
	v_add_f32_e32 v8, v8, v18
	ds_bpermute_b32 v18, v5, v8
	s_waitcnt lgkmcnt(0)
	v_add_f32_e32 v8, v8, v18
	ds_bpermute_b32 v18, v6, v8
	s_waitcnt lgkmcnt(0)
	v_add_f32_e32 v8, v8, v18
	ds_bpermute_b32 v18, v7, v8
	s_waitcnt lgkmcnt(0)
	v_add_f32_e32 v8, v8, v18
	v_fmac_f32_e32 v13, 0xbb000000, v8
	v_fmac_f32_e32 v12, 0xbb000000, v8
	v_mul_f32_e32 v13, v13, v13
	v_fmac_f32_e32 v14, 0xbb000000, v8
	v_fmac_f32_e32 v13, v12, v12
	v_fmac_f32_e32 v9, 0xbb000000, v8
	v_fmac_f32_e32 v13, v14, v14
	v_fmac_f32_e32 v15, 0xbb000000, v8
	v_fmac_f32_e32 v13, v9, v9
	v_fmac_f32_e32 v10, 0xbb000000, v8
	v_fmac_f32_e32 v13, v15, v15
	v_fmac_f32_e32 v16, 0xbb000000, v8
	v_fmac_f32_e32 v13, v10, v10
	v_fmac_f32_e32 v13, v16, v16
	v_fmac_f32_e32 v11, 0xbb000000, v8
	v_fmac_f32_e32 v13, v11, v11
	ds_bpermute_b32 v9, v2, v13
	s_waitcnt lgkmcnt(0)
	v_add_f32_e32 v9, v13, v9
	ds_bpermute_b32 v10, v3, v9
	s_waitcnt lgkmcnt(0)
	v_add_f32_e32 v9, v9, v10
	ds_bpermute_b32 v10, v4, v9
	s_waitcnt lgkmcnt(0)
	v_add_f32_e32 v9, v9, v10
	ds_bpermute_b32 v10, v5, v9
	s_waitcnt lgkmcnt(0)
	v_add_f32_e32 v9, v9, v10
	ds_bpermute_b32 v10, v6, v9
	s_waitcnt lgkmcnt(0)
	v_add_f32_e32 v9, v9, v10
	ds_bpermute_b32 v10, v7, v9
	s_and_saveexec_b64 s[44:45], s[4:5]
	s_cbranch_execz .LBB0_821
	s_waitcnt lgkmcnt(0)
	v_add_f32_e32 v9, v9, v10
	v_fmamk_f32 v9, v9, 0x3b000000, v238
	v_mul_f32_e32 v10, 0x4f800000, v9
	v_cmp_gt_f32_e32 vcc, s82, v9
	v_mul_f32_e32 v8, 0x3b000000, v8
	s_nop 0
	v_cndmask_b32_e32 v9, v9, v10, vcc
	v_sqrt_f32_e32 v10, v9
	s_nop 0
	v_add_u32_e32 v11, -1, v10
	v_fma_f32 v13, -v11, v10, v9
	v_add_u32_e32 v12, 1, v10
	v_cmp_ge_f32_e64 s[6:7], 0, v13
	s_nop 1
	v_cndmask_b32_e64 v11, v10, v11, s[6:7]
	v_fma_f32 v10, -v12, v10, v9
	v_cmp_lt_f32_e64 s[6:7], 0, v10
	s_nop 1
	v_cndmask_b32_e64 v10, v11, v12, s[6:7]
	v_mul_f32_e32 v11, 0x37800000, v10
	v_cndmask_b32_e32 v10, v10, v11, vcc
	v_cmp_class_f32_e32 vcc, v9, v239
	s_nop 1
	v_cndmask_b32_e32 v9, v10, v9, vcc
	s_add_i32 s6, s46, s47
	s_add_i32 s6, s6, 0x23490
	v_rcp_f32_e32 v9, v9
	v_mov_b32_e32 v10, s6
	ds_write_b64 v10, v[8:9]
.LBB0_821:
	s_or_b64 exec, exec, s[44:45]
	s_add_i32 s6, s42, 2
	s_ashr_i32 s7, s6, 31
	s_lshl_b64 s[6:7], s[6:7], 10
	v_lshl_add_u64 v[8:9], v[184:185], 0, s[6:7]
	s_waitcnt lgkmcnt(0)
	global_load_dwordx4 v[8:11], v[8:9], off
	s_waitcnt vmcnt(0)
	v_lshlrev_b32_e32 v12, 16, v8
	v_and_b32_e32 v13, 0xffff0000, v8
	v_add_f32_e32 v8, 0, v12
	v_lshlrev_b32_e32 v14, 16, v9
	v_add_f32_e32 v8, v8, v13
	v_and_b32_e32 v9, 0xffff0000, v9
	v_add_f32_e32 v8, v8, v14
	v_lshlrev_b32_e32 v15, 16, v10
	v_add_f32_e32 v8, v8, v9
	v_and_b32_e32 v10, 0xffff0000, v10
	v_add_f32_e32 v8, v8, v15
	v_lshlrev_b32_e32 v16, 16, v11
	v_add_f32_e32 v8, v8, v10
	v_and_b32_e32 v11, 0xffff0000, v11
	v_add_f32_e32 v8, v8, v16
	v_add_f32_e32 v8, v8, v11
	ds_bpermute_b32 v18, v2, v8
	s_waitcnt lgkmcnt(0)
	v_add_f32_e32 v8, v8, v18
	ds_bpermute_b32 v18, v3, v8
	s_waitcnt lgkmcnt(0)
	v_add_f32_e32 v8, v8, v18
	ds_bpermute_b32 v18, v4, v8
	s_waitcnt lgkmcnt(0)
	v_add_f32_e32 v8, v8, v18
	ds_bpermute_b32 v18, v5, v8
	s_waitcnt lgkmcnt(0)
	v_add_f32_e32 v8, v8, v18
	ds_bpermute_b32 v18, v6, v8
	s_waitcnt lgkmcnt(0)
	v_add_f32_e32 v8, v8, v18
	ds_bpermute_b32 v18, v7, v8
	s_waitcnt lgkmcnt(0)
	v_add_f32_e32 v8, v8, v18
	v_fmac_f32_e32 v13, 0xbb000000, v8
	v_fmac_f32_e32 v12, 0xbb000000, v8
	v_mul_f32_e32 v13, v13, v13
	v_fmac_f32_e32 v14, 0xbb000000, v8
	v_fmac_f32_e32 v13, v12, v12
	v_fmac_f32_e32 v9, 0xbb000000, v8
	v_fmac_f32_e32 v13, v14, v14
	v_fmac_f32_e32 v15, 0xbb000000, v8
	v_fmac_f32_e32 v13, v9, v9
	v_fmac_f32_e32 v10, 0xbb000000, v8
	v_fmac_f32_e32 v13, v15, v15
	v_fmac_f32_e32 v16, 0xbb000000, v8
	v_fmac_f32_e32 v13, v10, v10
	v_fmac_f32_e32 v13, v16, v16
	v_fmac_f32_e32 v11, 0xbb000000, v8
	v_fmac_f32_e32 v13, v11, v11
	ds_bpermute_b32 v9, v2, v13
	s_waitcnt lgkmcnt(0)
	v_add_f32_e32 v9, v13, v9
	ds_bpermute_b32 v10, v3, v9
	s_waitcnt lgkmcnt(0)
	v_add_f32_e32 v9, v9, v10
	ds_bpermute_b32 v10, v4, v9
	s_waitcnt lgkmcnt(0)
	v_add_f32_e32 v9, v9, v10
	ds_bpermute_b32 v10, v5, v9
	s_waitcnt lgkmcnt(0)
	v_add_f32_e32 v9, v9, v10
	ds_bpermute_b32 v10, v6, v9
	s_waitcnt lgkmcnt(0)
	v_add_f32_e32 v9, v9, v10
	ds_bpermute_b32 v10, v7, v9
	s_and_saveexec_b64 s[42:43], s[4:5]
	s_cbranch_execz .LBB0_814
	s_waitcnt lgkmcnt(0)
	v_add_f32_e32 v9, v9, v10
	v_fmamk_f32 v9, v9, 0x3b000000, v238
	v_mul_f32_e32 v10, 0x4f800000, v9
	v_cmp_gt_f32_e32 vcc, s82, v9
	v_mul_f32_e32 v8, 0x3b000000, v8
	s_nop 0
	v_cndmask_b32_e32 v9, v9, v10, vcc
	v_sqrt_f32_e32 v10, v9
	s_nop 0
	v_add_u32_e32 v11, -1, v10
	v_fma_f32 v13, -v11, v10, v9
	v_add_u32_e32 v12, 1, v10
	v_cmp_ge_f32_e64 s[6:7], 0, v13
	s_nop 1
	v_cndmask_b32_e64 v11, v10, v11, s[6:7]
	v_fma_f32 v10, -v12, v10, v9
	v_cmp_lt_f32_e64 s[6:7], 0, v10
	s_nop 1
	v_cndmask_b32_e64 v10, v11, v12, s[6:7]
	v_mul_f32_e32 v11, 0x37800000, v10
	v_cndmask_b32_e32 v10, v10, v11, vcc
	v_cmp_class_f32_e32 vcc, v9, v239
	s_nop 1
	v_cndmask_b32_e32 v9, v10, v9, vcc
	s_add_i32 s6, s46, s47
	s_add_i32 s6, s6, 0x23498
	v_rcp_f32_e32 v9, v9
	v_mov_b32_e32 v10, s6
	ds_write_b64 v10, v[8:9]
	s_branch .LBB0_814

.LBB0_910:
	s_or_b32 s4, s60, 4
	s_load_dword s5, s[0:1], 0xc8
	s_waitcnt lgkmcnt(0)
	s_cmp_gt_i32 s5, s4
	s_cbranch_scc1 .LBB0_1964
	s_load_dword s5, s[0:1], 0xcc
	s_waitcnt lgkmcnt(0)
	s_cmp_ge_i32 s4, s5
	s_cbranch_scc1 .LBB0_1964
	v_writelane_b32 v255, s60, 13
	s_load_dwordx2 s[4:5], s[0:1], 0xc0
	s_waitcnt lgkmcnt(0)
	s_lshl_b32 s6, s33, 6
	v_writelane_b32 v255, s4, 42
	s_nop 1
	v_writelane_b32 v255, s5, 43
	s_load_dwordx2 s[4:5], s[0:1], 0xb8
	s_waitcnt lgkmcnt(0)
	s_nop 0
	v_writelane_b32 v255, s4, 26
	s_nop 1
	v_writelane_b32 v255, s5, 27
	s_mov_b32 s4, s80
	s_load_dword s92, s[0:1], 0xd4
	s_waitcnt lgkmcnt(0)
	v_mbcnt_lo_u32_b32 v0, -1, 0
	v_mbcnt_hi_u32_b32 v0, -1, v0
	s_nop 0
	v_writelane_b32 v255, s4, 30
	v_writelane_b32 v255, s6, 34
	v_add_u32_e32 v157, s6, v0
	s_mov_b32 s4, 1
	s_cmp_lt_i32 s4, 1
	v_writelane_b32 v255, s4, 14
	s_cbranch_scc1 .LBB0_1423
	s_add_i32 s57, s97, 0x23800
	s_add_i32 s60, s97, 0x2380c
	s_add_i32 s61, s97, 0x23808
	s_add_i32 s62, s97, 0x23804
	v_readlane_b32 s4, v255, 30
	s_cmpk_lt_i32 s4, 0x200
	s_cselect_b64 s[4:5], -1, 0
	s_nop 1
	v_writelane_b32 v255, s4, 16
	s_mov_b32 s30, 0
	s_nop 0
	v_writelane_b32 v255, s5, 17
	s_nop 0
	v_readlane_b32 s6, v255, 42
	v_readlane_b32 s7, v255, 43
	s_add_u32 s34, s6, 0xe500000
	s_addc_u32 s35, s7, 0
	s_add_u32 s36, s6, 0xf600000
	s_addc_u32 s37, s7, 0
	s_add_u32 s63, s6, 0x13b00000
	s_addc_u32 s64, s7, 0
	s_add_u32 s65, s6, 0x13b80000
	s_addc_u32 s86, s7, 0
	s_add_u32 s38, s6, 0x13900000
	s_addc_u32 s39, s7, 0
	v_readlane_b32 s4, v255, 2
	v_readlane_b32 s5, v255, 3
	s_add_u32 s4, s6, s4
	s_addc_u32 s5, s7, s5
	s_add_u32 s87, s4, 0x24000000
	s_addc_u32 s88, s5, 0
	s_add_u32 s89, s6, 0x10700000
	s_addc_u32 s90, s7, 0
	s_add_u32 s91, s6, 0x10b00000
	s_addc_u32 s94, s7, 0
	s_add_u32 s95, s6, 0x10f00000
	s_addc_u32 s28, s7, 0
	s_add_u32 s29, s6, 0x11300000
	s_addc_u32 s93, s7, 0
	s_add_u32 s40, s6, 0x14400000
	s_addc_u32 s41, s7, 0
	s_branch .LBB0_915

.LBB0_925:
	ds_read_b128 v[12:15], v9
	ds_read_b128 v[22:25], v9 offset:64
	ds_read_b128 v[26:29], v9 offset:2304
	ds_read_b128 v[50:53], v9 offset:2368
	ds_read_b128 v[54:57], v9 offset:4608
	ds_read_b128 v[58:61], v9 offset:4672
	ds_read_b128 v[62:65], v9 offset:6912
	ds_read_b128 v[66:69], v9 offset:6976
	s_waitcnt vmcnt(1) lgkmcnt(7)
	v_mfma_f32_16x16x32_bf16 v[12:15], v[12:15], v[4:7], 0
	v_add_u32_e32 v10, s8, v153
	v_cmp_lt_i32_e32 vcc, v10, v20
	s_add_i32 s8, s8, 64
	s_waitcnt vmcnt(0) lgkmcnt(6)
	v_mfma_f32_16x16x32_bf16 v[12:15], v[22:25], v[0:3], v[12:15]
	v_add_u32_e32 v9, 0x2400, v9
	s_cmp_eq_u32 s76, s8
	s_waitcnt lgkmcnt(5)
	v_mfma_f32_16x16x32_bf16 v[22:25], v[26:29], v[4:7], 0
	s_waitcnt lgkmcnt(4)
	s_nop 0
	v_mfma_f32_16x16x32_bf16 v[22:25], v[50:53], v[0:3], v[22:25]
	s_nop 1
	v_cndmask_b32_e32 v16, v246, v12, vcc
	v_add_u32_e32 v12, 1, v10
	v_cmp_lt_i32_e32 vcc, v12, v20
	s_waitcnt lgkmcnt(3)
	v_mfma_f32_16x16x32_bf16 v[26:29], v[54:57], v[4:7], 0
	v_cndmask_b32_e32 v21, v246, v13, vcc
	v_add_u32_e32 v13, 2, v10
	v_cmp_lt_i32_e32 vcc, v13, v20
	v_add_u32_e32 v13, 3, v10
	s_waitcnt lgkmcnt(2)
	v_mfma_f32_16x16x32_bf16 v[26:29], v[58:61], v[0:3], v[26:29]
	v_cndmask_b32_e32 v14, v246, v14, vcc
	v_cmp_lt_i32_e32 vcc, v13, v20
	v_add_u32_e32 v13, 16, v10
	s_waitcnt lgkmcnt(1)
	v_mfma_f32_16x16x32_bf16 v[50:53], v[62:65], v[4:7], 0
	v_cndmask_b32_e32 v15, v246, v15, vcc
	v_cmp_lt_i32_e32 vcc, v13, v20
	v_add_u32_e32 v13, 17, v10
	s_waitcnt lgkmcnt(0)
	v_mfma_f32_16x16x32_bf16 v[50:53], v[66:69], v[0:3], v[50:53]
	v_cndmask_b32_e32 v22, v246, v22, vcc
	v_cmp_lt_i32_e32 vcc, v13, v20
	v_add_u32_e32 v13, 18, v10
	v_max3_f32 v12, v16, s96, v21
	v_cndmask_b32_e32 v23, v246, v23, vcc
	v_cmp_lt_i32_e32 vcc, v13, v20
	v_add_u32_e32 v13, 19, v10
	v_max3_f32 v12, v12, v14, v15
	v_cndmask_b32_e32 v24, v246, v24, vcc
	v_cmp_lt_i32_e32 vcc, v13, v20
	v_add_u32_e32 v13, 32, v10
	v_max3_f32 v12, v12, v22, v23
	v_cndmask_b32_e32 v25, v246, v25, vcc
	v_cmp_lt_i32_e32 vcc, v13, v20
	v_add_u32_e32 v13, 33, v10
	v_max3_f32 v12, v12, v24, v25
	v_cndmask_b32_e32 v26, v246, v26, vcc
	v_cmp_lt_i32_e32 vcc, v13, v20
	v_add_u32_e32 v13, 34, v10
	s_nop 0
	v_cndmask_b32_e32 v27, v246, v27, vcc
	v_cmp_lt_i32_e32 vcc, v13, v20
	v_add_u32_e32 v13, 35, v10
	v_max3_f32 v12, v12, v26, v27
	v_cndmask_b32_e32 v28, v246, v28, vcc
	v_cmp_lt_i32_e32 vcc, v13, v20
	v_add_u32_e32 v13, 48, v10
	s_nop 0
	v_cndmask_b32_e32 v29, v246, v29, vcc
	v_cmp_lt_i32_e32 vcc, v13, v20
	v_add_u32_e32 v13, 49, v10
	v_max3_f32 v12, v12, v28, v29
	v_cndmask_b32_e32 v33, v246, v50, vcc
	v_cmp_lt_i32_e32 vcc, v13, v20
	s_nop 1
	v_cndmask_b32_e32 v35, v246, v51, vcc
	v_max3_f32 v13, v12, v33, v35
	v_add_u32_e32 v12, 50, v10
	v_cmp_lt_i32_e32 vcc, v12, v20
	v_add_u32_e32 v10, 51, v10
	s_nop 0
	v_cndmask_b32_e32 v37, v246, v52, vcc
	v_cmp_lt_i32_e32 vcc, v10, v20
	s_nop 1
	v_cndmask_b32_e32 v12, v246, v53, vcc
	v_max3_f32 v10, v13, v37, v12
	v_mov_b32_e32 v13, v10
	s_nop 1
	v_permlane16_swap_b32_e32 v10, v13
	v_max_f32_e32 v13, v13, v13
	v_max_f32_e32 v10, v10, v10
	v_max_f32_e32 v10, v10, v13
	v_mov_b32_e32 v13, v10
	s_nop 1
	v_permlane32_swap_b32_e32 v10, v13
	v_max3_f32 v10, v11, v10, v13
	v_max_f32_e32 v13, 0xe0ad78ec, v10
	v_pk_mul_f32 v[18:19], v[12:13], s[70:71] op_sel_hi:[1,0]
	v_sub_f32_e32 v11, v11, v10
	v_fma_f32 v12, v16, s70, -v19
	v_exp_f32_e32 v12, v12
	v_fma_f32 v13, v21, s70, -v19
	v_exp_f32_e32 v13, v13
	v_mul_f32_e32 v11, 0x3e38aa3b, v11
	v_add_f32_e32 v12, 0, v12
	v_exp_f32_e32 v11, v11
	v_add_f32_e32 v12, v13, v12
	v_fma_f32 v13, v14, s70, -v19
	v_exp_f32_e32 v13, v13
	s_nop 0
	v_add_f32_e32 v12, v13, v12
	v_fma_f32 v13, v15, s70, -v19
	v_exp_f32_e32 v13, v13
	s_nop 0
	v_add_f32_e32 v12, v13, v12
	v_fma_f32 v13, v22, s70, -v19
	v_exp_f32_e32 v13, v13
	s_nop 0
	v_add_f32_e32 v12, v13, v12
	v_fma_f32 v13, v23, s70, -v19
	v_exp_f32_e32 v13, v13
	s_nop 0
	v_add_f32_e32 v12, v13, v12
	v_fma_f32 v13, v24, s70, -v19
	v_exp_f32_e32 v13, v13
	s_nop 0
	v_add_f32_e32 v12, v13, v12
	v_fma_f32 v13, v25, s70, -v19
	v_exp_f32_e32 v13, v13
	s_nop 0
	v_add_f32_e32 v12, v13, v12
	v_fma_f32 v13, v26, s70, -v19
	v_exp_f32_e32 v13, v13
	s_nop 0
	v_add_f32_e32 v12, v13, v12
	v_fma_f32 v13, v27, s70, -v19
	v_exp_f32_e32 v13, v13
	s_nop 0
	v_add_f32_e32 v12, v13, v12
	v_fma_f32 v13, v28, s70, -v19
	v_exp_f32_e32 v13, v13
	s_nop 0
	v_add_f32_e32 v12, v13, v12
	v_fma_f32 v13, v29, s70, -v19
	v_exp_f32_e32 v13, v13
	s_nop 0
	v_add_f32_e32 v12, v13, v12
	v_fma_f32 v13, v33, s70, -v19
	v_exp_f32_e32 v13, v13
	s_nop 0
	v_add_f32_e32 v12, v13, v12
	v_fma_f32 v13, v35, s70, -v19
	v_exp_f32_e32 v13, v13
	s_nop 0
	v_add_f32_e32 v12, v13, v12
	v_fma_f32 v13, v37, s70, -v19
	v_exp_f32_e32 v13, v13
	s_nop 0
	v_add_f32_e32 v12, v13, v12
	v_sub_f32_e32 v13, v18, v19
	v_exp_f32_e32 v13, v13
	s_nop 0
	v_add_f32_e32 v12, v13, v12
	v_mov_b32_e32 v13, v8
	v_mov_b32_e32 v8, v12
	v_fmac_f32_e32 v8, v13, v11
	v_mov_b32_e32 v11, v10
	s_cbranch_scc0 .LBB0_925
	v_mov_b32_e32 v9, v8
	s_nop 1
	v_permlane16_swap_b32_e32 v8, v9
	v_add_f32_e32 v12, v8, v9
	ds_read_b128 v[8:11], v38
	v_mov_b32_e32 v13, v12
	s_nop 1
	v_permlane32_swap_b32_e32 v12, v13
	v_add_f32_e32 v12, v12, v13
	v_max_f32_e32 v16, 0xda24260, v12
	ds_read_b128 v[12:15], v38 offset:64
	v_div_scale_f32 v18, s[8:9], v16, v16, 1.0
	v_rcp_f32_e32 v21, v18
	ds_read_b128 v[22:25], v38 offset:2304
	s_waitcnt lgkmcnt(2)
	v_mfma_f32_16x16x32_bf16 v[8:11], v[8:11], v[4:7], 0
	ds_read_b128 v[50:53], v38 offset:4672
	v_fma_f32 v26, -v18, v21, 1.0
	v_fmac_f32_e32 v21, v26, v21
	ds_read_b128 v[26:29], v38 offset:2368
	s_waitcnt lgkmcnt(3)
	v_mfma_f32_16x16x32_bf16 v[8:11], v[12:15], v[0:3], v[8:11]
	ds_read_b128 v[12:15], v38 offset:4608
	v_div_scale_f32 v33, vcc, 1.0, v16, 1.0
	s_waitcnt lgkmcnt(3)
	v_mfma_f32_16x16x32_bf16 v[22:25], v[22:25], v[4:7], 0
	v_mul_f32_e32 v35, v33, v21
	v_fma_f32 v37, -v18, v35, v33
	s_nop 1
	v_fma_f32 v8, v8, s70, -v19
	s_waitcnt lgkmcnt(1)
	v_mfma_f32_16x16x32_bf16 v[22:25], v[26:29], v[0:3], v[22:25]
	v_fmac_f32_e32 v35, v37, v21
	v_exp_f32_e32 v8, v8
	v_fma_f32 v9, v9, s70, -v19
	s_waitcnt lgkmcnt(0)
	v_mfma_f32_16x16x32_bf16 v[12:15], v[12:15], v[4:7], 0
	v_fma_f32 v18, -v18, v35, v33
	v_exp_f32_e32 v9, v9
	v_fma_f32 v10, v10, s70, -v19
	v_div_fmas_f32 v18, v18, v21, v35
	v_exp_f32_e32 v10, v10
	v_fma_f32 v11, v11, s70, -v19
	v_div_fixup_f32 v16, v18, v16, 1.0
	v_mfma_f32_16x16x32_bf16 v[12:15], v[50:53], v[0:3], v[12:15]
	v_exp_f32_e32 v11, v11
	v_fma_f32 v21, v22, s70, -v19
	v_mul_f32_e32 v8, v16, v8
	v_cmp_lt_i32_e32 vcc, v153, v20
	v_or_b32_e32 v154, 1, v153
	v_exp_f32_e32 v21, v21
	v_fma_f32 v22, v23, s70, -v19
	v_cndmask_b32_e32 v8, 0, v8, vcc
	v_mul_f32_e32 v9, v16, v9
	v_cmp_lt_i32_e32 vcc, v154, v20
	v_or_b32_e32 v155, 2, v153
	v_exp_f32_e32 v22, v22
	v_fma_f32 v23, v24, s70, -v19
	ds_read_b128 v[26:29], v38 offset:6912
	ds_read_b128 v[54:57], v38 offset:6976
	v_cndmask_b32_e32 v9, 0, v9, vcc
	v_mul_f32_e32 v10, v16, v10
	v_cmp_lt_i32_e32 vcc, v155, v20
	v_or_b32_e32 v156, 3, v153
	v_exp_f32_e32 v23, v23
	v_fma_f32 v24, v25, s70, -v19
	v_cndmask_b32_e32 v10, 0, v10, vcc
	v_mul_f32_e32 v11, v16, v11
	v_cmp_lt_i32_e32 vcc, v156, v20
	v_or_b32_e32 v158, 16, v153
	v_exp_f32_e32 v24, v24
	v_fma_f32 v12, v12, s70, -v19
	v_cndmask_b32_e32 v11, 0, v11, vcc
	v_mul_f32_e32 v21, v16, v21
	v_cmp_lt_i32_e32 vcc, v158, v20
	v_or_b32_e32 v159, 17, v153
	v_exp_f32_e32 v12, v12
	v_fma_f32 v13, v13, s70, -v19
	v_cndmask_b32_e32 v21, 0, v21, vcc
	v_mul_f32_e32 v22, v16, v22
	v_cmp_lt_i32_e32 vcc, v159, v20
	v_or_b32_e32 v160, 18, v153
	v_exp_f32_e32 v13, v13
	v_cndmask_b32_e32 v22, 0, v22, vcc
	v_mul_f32_e32 v23, v16, v23
	v_cmp_lt_i32_e32 vcc, v160, v20
	v_or_b32_e32 v161, 19, v153
	v_mul_f32_e32 v24, v16, v24
	v_cndmask_b32_e32 v23, 0, v23, vcc
	v_cmp_lt_i32_e32 vcc, v161, v20
	v_or_b32_e32 v162, 32, v153
	v_mul_f32_e32 v12, v16, v12
	v_cndmask_b32_e32 v24, 0, v24, vcc
	v_cmp_lt_i32_e32 vcc, v162, v20
	s_waitcnt lgkmcnt(1)
	v_mfma_f32_16x16x32_bf16 v[26:29], v[26:29], v[4:7], 0
	v_or_b32_e32 v163, 33, v153
	v_cndmask_b32_e32 v33, 0, v12, vcc
	v_mul_f32_e32 v12, v16, v13
	v_fma_f32 v13, v14, s70, -v19
	v_exp_f32_e32 v13, v13
	v_cmp_lt_i32_e32 vcc, v163, v20
	s_waitcnt lgkmcnt(0)
	v_mfma_f32_16x16x32_bf16 v[26:29], v[54:57], v[0:3], v[26:29]
	v_or_b32_e32 v164, 34, v153
	v_cndmask_b32_e32 v37, 0, v12, vcc
	v_mul_f32_e32 v12, v16, v13
	v_fma_f32 v13, v15, s70, -v19
	v_exp_f32_e32 v13, v13
	v_cmp_lt_i32_e32 vcc, v164, v20
	v_or_b32_e32 v165, 35, v153
	v_or_b32_e32 v166, 48, v153
	v_cndmask_b32_e32 v41, 0, v12, vcc
	v_mul_f32_e32 v12, v16, v13
	v_fma_f32 v13, v26, s70, -v19
	v_exp_f32_e32 v13, v13
	v_cmp_lt_i32_e32 vcc, v165, v20
	v_or_b32_e32 v167, 49, v153
	v_or_b32_e32 v168, 50, v153
	v_cndmask_b32_e32 v51, 0, v12, vcc
	v_mul_f32_e32 v12, v16, v13
	v_fma_f32 v13, v27, s70, -v19
	v_exp_f32_e32 v13, v13
	v_cmp_lt_i32_e32 vcc, v166, v20
	v_or_b32_e32 v169, 51, v153
	v_lshlrev_b32_e32 v48, 3, v44
	v_cndmask_b32_e32 v63, 0, v12, vcc
	v_mul_f32_e32 v12, v16, v13
	v_fma_f32 v13, v28, s70, -v19
	v_exp_f32_e32 v13, v13
	v_cmp_lt_i32_e32 vcc, v167, v20
	v_and_b32_e32 v18, 24, v48
	v_or_b32_e32 v47, v153, v42
	v_cndmask_b32_e32 v68, 0, v12, vcc
	v_mul_f32_e32 v12, v16, v13
	v_fma_f32 v13, v29, s70, -v19
	v_exp_f32_e32 v13, v13
	v_cmp_lt_i32_e32 vcc, v168, v20
	v_add_u32_e32 v39, s97, v18
	s_movk_i32 s8, 0x90
	v_cndmask_b32_e32 v69, 0, v12, vcc
	v_mul_f32_e32 v12, v16, v13
	v_cmp_lt_i32_e32 vcc, v169, v20
	v_cvt_pk_bf16_f32 v26, v8, v9
	v_cvt_pk_bf16_f32 v27, v10, v11
	v_cvt_pk_bf16_f32 v28, v21, v22
	v_cvt_pk_bf16_f32 v29, v23, v24
	v_cvt_pk_bf16_f32 v72, v33, v37
	s_nop 1
	v_cndmask_b32_e32 v71, 0, v12, vcc
	v_add_f32_e32 v12, v8, v9
	v_cvt_pk_bf16_f32 v73, v41, v51
	v_cvt_pk_bf16_f32 v74, v63, v68
	v_cvt_pk_bf16_f32 v75, v69, v71
	v_mad_u32_u24 v40, v47, s8, v39
	s_nop 0
	v_add_f32_dpp v56, v12, v12 quad_perm:[1,0,3,2] row_mask:0xf bank_mask:0xf bound_ctrl:1
	v_add_f32_e32 v12, v10, v11
	v_add_f32_e32 v18, v33, v37
	v_mov_b32_e32 v58, 0
	v_add_f32_dpp v52, v12, v12 quad_perm:[1,0,3,2] row_mask:0xf bank_mask:0xf bound_ctrl:1
	v_add_f32_e32 v12, v21, v22
	v_add_f32_dpp v60, v18, v18 quad_perm:[1,0,3,2] row_mask:0xf bank_mask:0xf bound_ctrl:1
	v_add_f32_e32 v18, v41, v51
	v_add_f32_dpp v57, v12, v12 quad_perm:[1,0,3,2] row_mask:0xf bank_mask:0xf bound_ctrl:1
	v_add_f32_e32 v12, v23, v24
	v_add_f32_dpp v53, v18, v18 quad_perm:[1,0,3,2] row_mask:0xf bank_mask:0xf bound_ctrl:1
	v_add_f32_e32 v18, v63, v68
	v_add_f32_dpp v62, v12, v12 quad_perm:[1,0,3,2] row_mask:0xf bank_mask:0xf bound_ctrl:1
	ds_read_b64_tr_b16 v[10:11], v40 offset:39168
	ds_read_b64_tr_b16 v[12:13], v40 offset:41472
	ds_read_b64_tr_b16 v[14:15], v40 offset:43776
	ds_read_b64_tr_b16 v[8:9], v40 offset:36864
	ds_read_b64_tr_b16 v[22:23], v40 offset:36896
	ds_read_b64_tr_b16 v[64:65], v40 offset:36928
	ds_read_b64_tr_b16 v[76:77], v40 offset:36960
	ds_read_b64_tr_b16 v[24:25], v40 offset:39200
	ds_read_b64_tr_b16 v[66:67], v40 offset:39232
	ds_read_b64_tr_b16 v[78:79], v40 offset:39264
	ds_read_b64_tr_b16 v[80:81], v40 offset:41504
	ds_read_b64_tr_b16 v[84:85], v40 offset:41536
	ds_read_b64_tr_b16 v[88:89], v40 offset:41568
	s_waitcnt lgkmcnt(9)
	v_mfma_f32_16x16x32_bf16 v[8:11], v[8:11], v[26:29], 0
	ds_read_b64_tr_b16 v[82:83], v40 offset:43808
	ds_read_b64_tr_b16 v[86:87], v40 offset:43840
	ds_read_b64_tr_b16 v[90:91], v40 offset:43872
	v_add_f32_dpp v63, v18, v18 quad_perm:[1,0,3,2] row_mask:0xf bank_mask:0xf bound_ctrl:1
	v_add_f32_e32 v18, v69, v71
	v_mfma_f32_16x16x32_bf16 v[8:11], v[12:15], v[72:75], v[8:11]
	v_mov_b32_e32 v54, 0
	v_mov_b32_e32 v59, 0
	v_mov_b32_e32 v70, 0
	s_waitcnt lgkmcnt(8)
	v_mfma_f32_16x16x32_bf16 v[12:15], v[22:25], v[26:29], 0
	v_mov_b32_e32 v61, 0
	v_mov_b32_e32 v55, 0
	v_lshlrev_b32_e32 v50, 1, v43
	s_waitcnt lgkmcnt(7)
	v_mfma_f32_16x16x32_bf16 v[22:25], v[64:67], v[26:29], 0
	v_mov_b32_e32 v64, 0
	v_add_f32_dpp v65, v18, v18 quad_perm:[1,0,3,2] row_mask:0xf bank_mask:0xf bound_ctrl:1
	v_mov_b32_e32 v66, 0
	s_waitcnt lgkmcnt(6)
	v_mfma_f32_16x16x32_bf16 v[26:29], v[76:79], v[26:29], 0
	s_add_i32 s56, s79, -2
	v_mov_b32_e32 v35, 0
	v_mov_b32_dpp v58, v56 quad_perm:[2,3,0,1] row_mask:0xf bank_mask:0xf
	s_waitcnt lgkmcnt(2)
	v_mfma_f32_16x16x32_bf16 v[12:15], v[80:83], v[72:75], v[12:15]
	v_mov_b32_dpp v54, v52 quad_perm:[2,3,0,1] row_mask:0xf bank_mask:0xf
	v_mov_b32_dpp v59, v57 quad_perm:[2,3,0,1] row_mask:0xf bank_mask:0xf
	v_mov_b32_dpp v70, v62 quad_perm:[2,3,0,1] row_mask:0xf bank_mask:0xf
	s_waitcnt lgkmcnt(1)
	v_mfma_f32_16x16x32_bf16 v[22:25], v[84:87], v[72:75], v[22:25]
	v_mov_b32_dpp v61, v60 quad_perm:[2,3,0,1] row_mask:0xf bank_mask:0xf
	v_mov_b32_dpp v55, v53 quad_perm:[2,3,0,1] row_mask:0xf bank_mask:0xf
	v_mov_b32_dpp v64, v63 quad_perm:[2,3,0,1] row_mask:0xf bank_mask:0xf
	s_waitcnt lgkmcnt(0)
	v_mfma_f32_16x16x32_bf16 v[26:29], v[88:91], v[72:75], v[26:29]
	v_mov_b32_dpp v66, v65 quad_perm:[2,3,0,1] row_mask:0xf bank_mask:0xf
	s_and_b64 vcc, exec, s[42:43]
	s_cbranch_vccz .LBB0_930
	ds_read_b128 v[72:75], v38 offset:9216
	ds_read_b128 v[76:79], v38 offset:9280
	ds_read_b128 v[80:83], v38 offset:11520
	ds_read_b128 v[84:87], v38 offset:11584
	ds_read_b128 v[88:91], v38 offset:13824
	ds_read_b128 v[92:95], v38 offset:13888
	ds_read_b128 v[96:99], v38 offset:16128
	ds_read_b128 v[100:103], v38 offset:16192
	v_or_b32_e32 v18, 0x42, v153
	s_waitcnt lgkmcnt(7)
	v_mfma_f32_16x16x32_bf16 v[72:75], v[72:75], v[4:7], 0
	v_or_b32_e32 v21, 64, v153
	v_cmp_lt_i32_e32 vcc, v18, v20
	v_or_b32_e32 v33, 0x43, v153
	s_waitcnt lgkmcnt(6)
	v_mfma_f32_16x16x32_bf16 v[72:75], v[76:79], v[0:3], v[72:75]
	v_or_b32_e32 v37, 0x41, v153
	v_or_b32_e32 v51, 0x50, v153
	v_or_b32_e32 v71, 0x51, v153
	s_waitcnt lgkmcnt(5)
	v_mfma_f32_16x16x32_bf16 v[80:83], v[80:83], v[4:7], 0
	v_mov_b32_e32 v116, v17
	s_nop 1
	v_fma_f32 v41, v72, s70, -v19
	v_exp_f32_e32 v68, v41
	v_fma_f32 v41, v73, s70, -v19
	s_waitcnt lgkmcnt(4)
	v_mfma_f32_16x16x32_bf16 v[76:79], v[84:87], v[0:3], v[80:83]
	v_exp_f32_e32 v84, v41
	v_fma_f32 v41, v74, s70, -v19
	v_exp_f32_e32 v69, v41
	s_waitcnt lgkmcnt(3)
	v_mfma_f32_16x16x32_bf16 v[80:83], v[88:91], v[4:7], 0
	v_fma_f32 v41, v75, s70, -v19
	s_nop 1
	v_fma_f32 v77, v77, s70, -v19
	v_exp_f32_e32 v85, v41
	s_waitcnt lgkmcnt(1)
	v_mfma_f32_16x16x32_bf16 v[72:75], v[96:99], v[4:7], 0
	v_exp_f32_e32 v86, v77
	v_fma_f32 v77, v78, s70, -v19
	v_fma_f32 v78, v79, s70, -v19
	v_mfma_f32_16x16x32_bf16 v[80:83], v[92:95], v[0:3], v[80:83]
	v_exp_f32_e32 v87, v78
	v_pk_mul_f32 v[68:69], v[16:17], v[68:69] op_sel_hi:[0,1]
	v_fma_f32 v67, v76, s70, -v19
	s_waitcnt lgkmcnt(0)
	v_mfma_f32_16x16x32_bf16 v[72:75], v[100:103], v[0:3], v[72:75]
	v_exp_f32_e32 v76, v67
	s_nop 1
	v_fma_f32 v79, v81, s70, -v19
	v_fma_f32 v78, v80, s70, -v19
	v_exp_f32_e32 v80, v79
	v_fma_f32 v79, v82, s70, -v19
	s_nop 0
	v_fma_f32 v72, v72, s70, -v19
	v_exp_f32_e32 v82, v72
	v_fma_f32 v72, v73, s70, -v19
	v_exp_f32_e32 v88, v72
	v_fma_f32 v72, v74, s70, -v19
	v_fma_f32 v81, v83, s70, -v19
	v_exp_f32_e32 v83, v72
	v_fma_f32 v72, v75, s70, -v19
	v_cndmask_b32_e32 v75, 0, v69, vcc
	v_cmp_lt_i32_e32 vcc, v21, v20
	v_exp_f32_e32 v89, v72
	v_mov_b32_e32 v72, v17
	v_cndmask_b32_e32 v74, 0, v68, vcc
	v_pk_mul_f32 v[68:69], v[16:17], v[84:85] op_sel_hi:[0,1]
	v_cmp_lt_i32_e32 vcc, v33, v20
	v_mov_b32_e32 v73, v17
	v_exp_f32_e32 v77, v77
	v_cndmask_b32_e32 v85, 0, v69, vcc
	v_cmp_lt_i32_e32 vcc, v37, v20
	v_or_b32_e32 v91, 32, v50
	v_or_b32_e32 v90, 33, v50
	v_cndmask_b32_e32 v84, 0, v68, vcc
	v_pk_add_f32 v[68:69], v[74:75], v[84:85]
	v_cmp_ge_u32_e32 vcc, s56, v91
	v_or_b32_e32 v41, 0x52, v153
	v_mov_b32_dpp v72, v68 quad_perm:[1,0,3,2] row_mask:0xf bank_mask:0xf
	v_mov_b32_dpp v73, v69 quad_perm:[1,0,3,2] row_mask:0xf bank_mask:0xf
	v_pk_add_f32 v[68:69], v[68:69], v[72:73]
	v_mov_b32_e32 v72, v17
	v_mov_b32_e32 v73, v17
	v_or_b32_e32 v67, 0x53, v153
	v_mov_b32_dpp v72, v68 quad_perm:[2,3,0,1] row_mask:0xf bank_mask:0xf
	v_mov_b32_dpp v73, v69 quad_perm:[2,3,0,1] row_mask:0xf bank_mask:0xf
	v_pk_add_f32 v[68:69], v[68:69], v[72:73]
	v_pk_mul_f32 v[72:73], v[16:17], v[76:77] op_sel_hi:[0,1]
	v_and_b32_e32 v21, 0xffffff80, v68
	v_and_b32_e32 v18, 0xffffff80, v69
	v_or_b32_e32 v21, v21, v50
	v_or_b32_e32 v18, v18, v50
	v_xor_b32_e32 v21, 0x5f, v21
	v_xor_b32_e32 v18, 0x5e, v18
	v_cndmask_b32_e32 v68, 0, v21, vcc
	v_cmp_ge_u32_e32 vcc, s56, v90
	v_mov_b32_e32 v90, v17
	v_mov_b32_e32 v91, v17
	v_cndmask_b32_e32 v69, 0, v18, vcc
	v_cmp_lt_i32_e32 vcc, v41, v20
	v_exp_f32_e32 v78, v78
	v_exp_f32_e32 v79, v79
	v_cndmask_b32_e32 v77, 0, v73, vcc
	v_cmp_lt_i32_e32 vcc, v51, v20
	v_or_b32_e32 v21, 40, v50
	v_exp_f32_e32 v81, v81
	v_cndmask_b32_e32 v76, 0, v72, vcc
	v_pk_mul_f32 v[72:73], v[16:17], v[86:87] op_sel_hi:[0,1]
	v_cmp_lt_i32_e32 vcc, v67, v20
	v_or_b32_e32 v18, 41, v50
	v_or_b32_e32 v92, 0x62, v153
	v_cndmask_b32_e32 v87, 0, v73, vcc
	v_cmp_lt_i32_e32 vcc, v71, v20
	v_or_b32_e32 v93, 0x60, v153
	v_pk_mul_f32 v[78:79], v[16:17], v[78:79] op_sel_hi:[0,1]
	v_cndmask_b32_e32 v86, 0, v72, vcc
	v_pk_add_f32 v[72:73], v[76:77], v[86:87]
	v_cmp_ge_u32_e32 vcc, s56, v21
	v_or_b32_e32 v94, 0x63, v153
	v_mov_b32_dpp v90, v72 quad_perm:[1,0,3,2] row_mask:0xf bank_mask:0xf
	v_mov_b32_dpp v91, v73 quad_perm:[1,0,3,2] row_mask:0xf bank_mask:0xf
	v_pk_add_f32 v[72:73], v[72:73], v[90:91]
	v_mov_b32_e32 v90, v17
	v_mov_b32_e32 v91, v17
	v_or_b32_e32 v95, 0x61, v153
	v_mov_b32_dpp v90, v72 quad_perm:[2,3,0,1] row_mask:0xf bank_mask:0xf
	v_mov_b32_dpp v91, v73 quad_perm:[2,3,0,1] row_mask:0xf bank_mask:0xf
	v_pk_add_f32 v[72:73], v[72:73], v[90:91]
	v_pk_mul_f32 v[80:81], v[16:17], v[80:81] op_sel_hi:[0,1]
	v_and_b32_e32 v37, 0xffffff80, v72
	v_and_b32_e32 v33, 0xffffff80, v73
	v_or_b32_e32 v37, v37, v50
	v_or_b32_e32 v33, v33, v50
	v_xor_b32_e32 v37, 0x57, v37
	v_xor_b32_e32 v33, 0x56, v33
	v_cndmask_b32_e32 v73, 0, v37, vcc
	v_cmp_ge_u32_e32 vcc, s56, v18
	v_or_b32_e32 v21, 48, v50
	v_or_b32_e32 v18, 49, v50
	v_cndmask_b32_e32 v33, 0, v33, vcc
	v_cmp_lt_i32_e32 vcc, v92, v20
	v_mov_b32_e32 v92, v17
	v_or_b32_e32 v96, 0x72, v153
	v_cndmask_b32_e32 v79, 0, v79, vcc
	v_cmp_lt_i32_e32 vcc, v93, v20
	v_mov_b32_e32 v93, v17
	v_or_b32_e32 v97, 0x70, v153
	v_cndmask_b32_e32 v78, 0, v78, vcc
	v_cmp_lt_i32_e32 vcc, v94, v20
	v_pk_mul_f32 v[82:83], v[16:17], v[82:83] op_sel_hi:[0,1]
	v_or_b32_e32 v98, 0x73, v153
	v_cndmask_b32_e32 v81, 0, v81, vcc
	v_cmp_lt_i32_e32 vcc, v95, v20
	v_or_b32_e32 v99, 0x71, v153
	v_pk_mul_f32 v[88:89], v[16:17], v[88:89] op_sel_hi:[0,1]
	v_cndmask_b32_e32 v80, 0, v80, vcc
	v_pk_add_f32 v[90:91], v[78:79], v[80:81]
	v_cmp_ge_u32_e32 vcc, s56, v21
	v_cvt_pk_bf16_f32 v74, v74, v84
	v_cvt_pk_bf16_f32 v75, v75, v85
	v_cvt_pk_bf16_f32 v76, v76, v86
	v_cvt_pk_bf16_f32 v77, v77, v87
	s_nop 0
	v_mov_b32_dpp v92, v90 quad_perm:[1,0,3,2] row_mask:0xf bank_mask:0xf
	v_mov_b32_dpp v93, v91 quad_perm:[1,0,3,2] row_mask:0xf bank_mask:0xf
	v_pk_add_f32 v[90:91], v[90:91], v[92:93]
	v_mov_b32_e32 v92, v17
	v_mov_b32_e32 v93, v17
	v_cvt_pk_bf16_f32 v78, v78, v80
	v_cvt_pk_bf16_f32 v79, v79, v81
	v_mov_b32_e32 v117, v17
	v_mov_b32_dpp v92, v90 quad_perm:[2,3,0,1] row_mask:0xf bank_mask:0xf
	v_mov_b32_dpp v93, v91 quad_perm:[2,3,0,1] row_mask:0xf bank_mask:0xf
	v_pk_add_f32 v[90:91], v[90:91], v[92:93]
	v_or_b32_e32 v21, 56, v50
	v_and_b32_e32 v41, 0xffffff80, v90
	v_and_b32_e32 v37, 0xffffff80, v91
	v_or_b32_e32 v41, v41, v50
	v_or_b32_e32 v37, v37, v50
	v_xor_b32_e32 v41, 0x4f, v41
	v_xor_b32_e32 v37, 0x4e, v37
	v_cndmask_b32_e32 v71, 0, v41, vcc
	v_cmp_ge_u32_e32 vcc, s56, v18
	v_or_b32_e32 v18, 57, v50
	s_nop 0
	v_cndmask_b32_e32 v72, 0, v37, vcc
	v_cmp_lt_i32_e32 vcc, v96, v20
	s_nop 1
	v_cndmask_b32_e32 v83, 0, v83, vcc
	v_cmp_lt_i32_e32 vcc, v97, v20
	s_nop 1
	v_cndmask_b32_e32 v82, 0, v82, vcc
	v_cmp_lt_i32_e32 vcc, v98, v20
	s_nop 1
	v_cndmask_b32_e32 v89, 0, v89, vcc
	v_cmp_lt_i32_e32 vcc, v99, v20
	s_nop 1
	v_cndmask_b32_e32 v88, 0, v88, vcc
	v_cvt_pk_bf16_f32 v80, v82, v88
	v_cvt_pk_bf16_f32 v81, v83, v89
	v_pk_add_f32 v[114:115], v[82:83], v[88:89]
	ds_read_b64_tr_b16 v[84:85], v40 offset:48384
	ds_read_b64_tr_b16 v[86:87], v40 offset:50688
	ds_read_b64_tr_b16 v[88:89], v40 offset:52992
	ds_read_b64_tr_b16 v[82:83], v40 offset:46080
	ds_read_b64_tr_b16 v[90:91], v40 offset:46112
	ds_read_b64_tr_b16 v[94:95], v40 offset:46144
	ds_read_b64_tr_b16 v[98:99], v40 offset:46176
	ds_read_b64_tr_b16 v[92:93], v40 offset:48416
	ds_read_b64_tr_b16 v[96:97], v40 offset:48448
	ds_read_b64_tr_b16 v[100:101], v40 offset:48480
	ds_read_b64_tr_b16 v[102:103], v40 offset:50720
	ds_read_b64_tr_b16 v[106:107], v40 offset:50752
	ds_read_b64_tr_b16 v[110:111], v40 offset:50784
	ds_read_b64_tr_b16 v[104:105], v40 offset:53024
	ds_read_b64_tr_b16 v[108:109], v40 offset:53056
	ds_read_b64_tr_b16 v[112:113], v40 offset:53088
	v_mov_b32_dpp v116, v114 quad_perm:[1,0,3,2] row_mask:0xf bank_mask:0xf
	v_mov_b32_dpp v117, v115 quad_perm:[1,0,3,2] row_mask:0xf bank_mask:0xf
	s_waitcnt lgkmcnt(12)
	v_mfma_f32_16x16x32_bf16 v[8:11], v[82:85], v[74:77], v[8:11]
	v_add_f32_e64 v82, v114, v116
	v_add_f32_e64 v83, v115, v117
	v_mov_b32_e32 v84, v17
	v_mov_b32_e32 v85, v17
	s_waitcnt lgkmcnt(8)
	v_mfma_f32_16x16x32_bf16 v[12:15], v[90:93], v[74:77], v[12:15]
	v_mov_b32_dpp v84, v82 quad_perm:[2,3,0,1] row_mask:0xf bank_mask:0xf
	v_mov_b32_dpp v85, v83 quad_perm:[2,3,0,1] row_mask:0xf bank_mask:0xf
	v_pk_add_f32 v[82:83], v[82:83], v[84:85]
	s_waitcnt lgkmcnt(7)
	v_mfma_f32_16x16x32_bf16 v[22:25], v[94:97], v[74:77], v[22:25]
	v_and_b32_e32 v41, 0xffffff80, v82
	v_and_b32_e32 v37, 0xffffff80, v83
	v_or_b32_e32 v41, v41, v50
	s_waitcnt lgkmcnt(6)
	v_mfma_f32_16x16x32_bf16 v[26:29], v[98:101], v[74:77], v[26:29]
	v_or_b32_e32 v37, v37, v50
	v_xor_b32_e32 v41, 0x47, v41
	v_cmp_ge_u32_e32 vcc, s56, v21
	v_mfma_f32_16x16x32_bf16 v[8:11], v[86:89], v[78:81], v[8:11]
	v_xor_b32_e32 v37, 0x46, v37
	v_cndmask_b32_e32 v75, 0, v41, vcc
	v_cmp_ge_u32_e32 vcc, s56, v18
	s_waitcnt lgkmcnt(2)
	v_mfma_f32_16x16x32_bf16 v[12:15], v[102:105], v[78:81], v[12:15]
	v_cndmask_b32_e32 v37, 0, v37, vcc
	s_waitcnt lgkmcnt(1)
	v_mfma_f32_16x16x32_bf16 v[22:25], v[106:109], v[78:81], v[22:25]
	s_waitcnt lgkmcnt(0)
	v_mfma_f32_16x16x32_bf16 v[26:29], v[110:113], v[78:81], v[26:29]
	s_branch .LBB0_931
